# stack: best + residual-epilogue rewrite (all h_old loads in flight, interleaved chains) + in-proj row-scale LDS burst + incremental next-tile coordinates
# speedup vs baseline: 1.0304x; 1.0040x over previous
;     __host__ __device__ bool next(int i, Unit& u) const {
;         const long L = (long)i * G + c; if (L >= nwg) return false;
;         int wgid = (int)L; { const int q = nwg / NXCD, r = nwg % NXCD, xcd = wgid % NXCD, off = wgid / NXCD; wgid = (xcd < r ? xcd * (q + 1) : r * (q + 1) + (xcd - r) * q) + off; }
;         const int nig = WGM * nN, gid = wgid / nig, fm = gid * WGM, gsz = (nM - fm) < WGM ? (nM - fm) : WGM;
;         u.pm = fm + ((wgid % nig) % gsz); u.pn = (wgid % nig) / gsz; return true;
;     }
; template <class Epi, class Sched, bool ALIGN_EPI = false, bool SP2 = false>
; __device__ __forceinline__ void gemm_phase(PG8_LAS unsigned char* lds, const Gemm g, const Sched& S, const Epi& E) {
;     ...
;         const bool has_next = S.next(ui + 1, nxt);
.LBB0_244:
	s_cmp_lg_u32 s88, 0x100
	s_cbranch_scc1 .Lsn_gen_0
	s_add_i32 s2, s2, 1
	s_cmp_lt_u32 s2, 12
	s_cselect_b64 s[6:7], -1, 0
	s_cbranch_scc0 .LBB0_246
	s_add_i32 s48, s50, 4
	s_mov_b32 s49, s22
	s_cmp_lt_u32 s48, 12
	s_cbranch_scc1 .LBB0_246
	s_sub_i32 s48, s48, 12
	s_add_i32 s49, s49, 8
	s_branch .LBB0_246

; __device__ __forceinline__ unsigned cvt_pk_bf16(float lo, float hi) { unsigned r; asm volatile("v_cvt_pk_bf16_f32 %0, %1, %2" : "=v"(r) : "v"(lo), "v"(hi)); return r; }
; #define LAS __attribute__((address_space(3)))
;     __device__ __forceinline__ void operator()(const f32x4 (&acc)[2][2][4][2], const pg8::Unit& u, int wr, int wc, int fr_, int fq_, LAS const unsigned char* xl) const {
;     ...
;                 for (int m = 0; m < 4; ++m) { const f32x4 pv = *(LAS const f32x4*)(xl + (ai * 128 + wr * 64 + m * 16 + fr) * 64 + fq * 16); rv[ai][m] = (pv[0] + pv[1]) + (pv[2] + pv[3]); }
; #pragma unroll
;             for (int ai = 0; ai < 2; ++ai)
; #pragma unroll
;                 for (int m = 0; m < 4; ++m) rv[ai][m] = __builtin_amdgcn_rsqf(xrow16_sum(rv[ai][m]) * (1.0f / 1024.0f) + EPS);
;         }
;         if (MODE == 0 || MODE == 1 || MODE == 2) {
; #pragma unroll
;             for (int ai = 0; ai < 2; ++ai)
; #pragma unroll
;                 for (int m = 0; m < 4; ++m) {
;                     const int row = row0 + ai * 128 + m * 16;
;                     const float rinv = (MODE == 2) ? 1.f : rv[ai][m];
;                     if (MODE == 0 || MODE == 2) {
;                         bf16_t* rowp = O + (size_t)row * ldc + u.pn * 256 + wc * 32 + 8 * fq;
; #pragma unroll
;                         for (int bj = 0; bj < 2; ++bj) { const f32x4 v0 = acc[ai][bj][m][0] * rinv, v1 = acc[ai][bj][m][1] * rinv;
;                             u32x4 w; w.x = pg8::cvt_pk_bf16(v0[0], v0[1]); w.y = pg8::cvt_pk_bf16(v0[2], v0[3]); w.z = pg8::cvt_pk_bf16(v1[0], v1[1]); w.w = pg8::cvt_pk_bf16(v1[2], v1[3]);
;                             *(u32x4*)(rowp + bj * 128) = w; }
.LBB0_265:
	v_mov_b32_e32 v133, v238
	v_add_u32_e32 v134, s46, v237
	v_lshlrev_b32_e32 v128, 4, v133
	v_lshlrev_b32_e32 v129, 6, v134
	s_add_i32 s23, 0, 0x20000
	v_add3_u32 v135, s23, v128, v129
	ds_read_b128 v[152:155], v135
	ds_read_b128 v[156:159], v135 offset:1024
	ds_read_b128 v[160:163], v135 offset:2048
	ds_read_b128 v[164:167], v135 offset:3072
	ds_read_b128 v[168:171], v135 offset:8192
	ds_read_b128 v[172:175], v135 offset:9216
	ds_read_b128 v[176:179], v135 offset:10240
	ds_read_b128 v[180:183], v135 offset:11264
	s_and_b64 vcc, exec, s[4:5]
	s_waitcnt lgkmcnt(0)
	v_add_f32_e32 v152, v152, v153
	v_add_f32_e32 v154, v154, v155
	v_add_f32_e32 v156, v156, v157
	v_add_f32_e32 v158, v158, v159
	v_add_f32_e32 v160, v160, v161
	v_add_f32_e32 v162, v162, v163
	v_add_f32_e32 v164, v164, v165
	v_add_f32_e32 v166, v166, v167
	v_add_f32_e32 v168, v168, v169
	v_add_f32_e32 v170, v170, v171
	v_add_f32_e32 v172, v172, v173
	v_add_f32_e32 v174, v174, v175
	v_add_f32_e32 v176, v176, v177
	v_add_f32_e32 v178, v178, v179
	v_add_f32_e32 v180, v180, v181
	v_add_f32_e32 v182, v182, v183
	v_add_f32_e32 v142, v152, v154
	v_add_f32_e32 v144, v156, v158
	v_add_f32_e32 v146, v160, v162
	v_add_f32_e32 v140, v164, v166
	v_add_f32_e32 v138, v168, v170
	v_add_f32_e32 v136, v172, v174
	v_add_f32_e32 v132, v176, v178
	v_add_f32_e32 v128, v180, v182
	v_mov_b32_e32 v152, v142
	v_mov_b32_e32 v153, v144
	v_mov_b32_e32 v154, v146
	v_mov_b32_e32 v155, v140
	v_mov_b32_e32 v156, v138
	v_mov_b32_e32 v157, v136
	v_mov_b32_e32 v158, v132
	v_mov_b32_e32 v159, v128
	v_permlane16_swap_b32_e32 v142, v152
	v_permlane16_swap_b32_e32 v144, v153
	v_permlane16_swap_b32_e32 v146, v154
	v_permlane16_swap_b32_e32 v140, v155
	v_permlane16_swap_b32_e32 v138, v156
	v_permlane16_swap_b32_e32 v136, v157
	v_permlane16_swap_b32_e32 v132, v158
	v_permlane16_swap_b32_e32 v128, v159
	v_add_f32_e32 v142, v142, v152
	v_add_f32_e32 v144, v144, v153
	v_add_f32_e32 v146, v146, v154
	v_add_f32_e32 v140, v140, v155
	v_add_f32_e32 v138, v138, v156
	v_add_f32_e32 v136, v136, v157
	v_add_f32_e32 v132, v132, v158
	v_add_f32_e32 v128, v128, v159
	v_mov_b32_e32 v152, v142
	v_mov_b32_e32 v153, v144
	v_mov_b32_e32 v154, v146
	v_mov_b32_e32 v155, v140
	v_mov_b32_e32 v156, v138
	v_mov_b32_e32 v157, v136
	v_mov_b32_e32 v158, v132
	v_mov_b32_e32 v159, v128
	v_permlane32_swap_b32_e32 v142, v152
	v_permlane32_swap_b32_e32 v144, v153
	v_permlane32_swap_b32_e32 v146, v154
	v_permlane32_swap_b32_e32 v140, v155
	v_permlane32_swap_b32_e32 v138, v156
	v_permlane32_swap_b32_e32 v136, v157
	v_permlane32_swap_b32_e32 v132, v158
	v_permlane32_swap_b32_e32 v128, v159
	v_add_f32_e32 v142, v142, v152
	v_add_f32_e32 v144, v144, v153
	v_add_f32_e32 v146, v146, v154
	v_add_f32_e32 v140, v140, v155
	v_add_f32_e32 v138, v138, v156
	v_add_f32_e32 v136, v136, v157
	v_add_f32_e32 v132, v132, v158
	v_add_f32_e32 v128, v128, v159
	v_fmamk_f32 v142, v142, 0x3a800000, v233
	v_fmamk_f32 v144, v144, 0x3a800000, v233
	v_fmamk_f32 v146, v146, 0x3a800000, v233
	v_fmamk_f32 v140, v140, 0x3a800000, v233
	v_fmamk_f32 v138, v138, 0x3a800000, v233
	v_fmamk_f32 v136, v136, 0x3a800000, v233
	v_fmamk_f32 v132, v132, 0x3a800000, v233
	v_rsq_f32_e32 v142, v142
	v_rsq_f32_e32 v144, v144
	v_rsq_f32_e32 v146, v146
	v_rsq_f32_e32 v140, v140
	v_rsq_f32_e32 v138, v138
	v_rsq_f32_e32 v136, v136
	v_rsq_f32_e32 v132, v132
	v_lshl_add_u32 v129, s22, 8, v134
	v_mov_b64_e32 v[130:131], s[72:73]
	v_mad_i64_i32 v[148:149], s[22:23], v129, s83, v[130:131]
	s_lshl_b32 s22, s50, 8
	s_ashr_i32 s23, s22, 31
	v_lshlrev_b32_e32 v134, 3, v133
	s_lshl_b64 s[22:23], s[22:23], 1
	v_ashrrev_i32_e32 v135, 31, v134
	v_lshl_add_u64 v[148:149], v[148:149], 0, s[22:23]
	v_lshl_add_u64 v[148:149], v[148:149], 0, s[86:87]
	v_lshlrev_b64 v[134:135], 1, v[134:135]
	v_lshl_add_u64 v[148:149], v[148:149], 0, v[134:135]
	v_pk_mul_f32 v[126:127], v[126:127], v[142:143] op_sel_hi:[1,0]
	v_pk_mul_f32 v[124:125], v[124:125], v[142:143] op_sel_hi:[1,0]
	v_pk_mul_f32 v[150:151], v[122:123], v[142:143] op_sel_hi:[1,0]
	v_pk_mul_f32 v[122:123], v[120:121], v[142:143] op_sel_hi:[1,0]
	v_cvt_pk_bf16_f32 v120, v124, v125
	v_cvt_pk_bf16_f32 v121, v126, v127
	v_pk_mul_f32 v[116:117], v[116:117], v[142:143] op_sel_hi:[1,0]
	v_cvt_pk_bf16_f32 v122, v122, v123
	v_cvt_pk_bf16_f32 v123, v150, v151
	global_store_dwordx4 v[148:149], v[120:123], off
	v_pk_mul_f32 v[118:119], v[118:119], v[142:143] op_sel_hi:[1,0]
	v_pk_mul_f32 v[110:111], v[110:111], v[144:145] op_sel_hi:[1,0]
	v_pk_mul_f32 v[120:121], v[114:115], v[142:143] op_sel_hi:[1,0]
	v_pk_mul_f32 v[114:115], v[112:113], v[142:143] op_sel_hi:[1,0]
	v_cvt_pk_bf16_f32 v112, v116, v117
	v_cvt_pk_bf16_f32 v113, v118, v119
	v_pk_mul_f32 v[108:109], v[108:109], v[144:145] op_sel_hi:[1,0]
	v_cvt_pk_bf16_f32 v114, v114, v115
	v_cvt_pk_bf16_f32 v115, v120, v121
	global_store_dwordx4 v[148:149], v[112:115], off offset:256
	v_pk_mul_f32 v[100:101], v[100:101], v[144:145] op_sel_hi:[1,0]
	v_pk_mul_f32 v[102:103], v[102:103], v[144:145] op_sel_hi:[1,0]
	v_add_u32_e32 v112, 16, v129
	v_mad_i64_i32 v[112:113], s[24:25], v112, s83, v[130:131]
	v_lshl_add_u64 v[112:113], v[112:113], 0, s[22:23]
	v_lshl_add_u64 v[112:113], v[112:113], 0, s[86:87]
	v_lshl_add_u64 v[112:113], v[112:113], 0, v[134:135]
	v_pk_mul_f32 v[114:115], v[106:107], v[144:145] op_sel_hi:[1,0]
	v_pk_mul_f32 v[106:107], v[104:105], v[144:145] op_sel_hi:[1,0]
	v_cvt_pk_bf16_f32 v104, v108, v109
	v_cvt_pk_bf16_f32 v105, v110, v111
	v_pk_mul_f32 v[94:95], v[94:95], v[146:147] op_sel_hi:[1,0]
	v_cvt_pk_bf16_f32 v106, v106, v107
	v_cvt_pk_bf16_f32 v107, v114, v115
	global_store_dwordx4 v[112:113], v[104:107], off
; __device__ __forceinline__ unsigned cvt_pk_bf16(float lo, float hi) { unsigned r; asm volatile("v_cvt_pk_bf16_f32 %0, %1, %2" : "=v"(r) : "v"(lo), "v"(hi)); return r; }
; #define PG8_BAR __builtin_amdgcn_s_barrier()
; template <class Epi, class Sched, bool ALIGN_EPI = false, bool SP2 = false>
; __device__ __forceinline__ void gemm_phase(PG8_LAS unsigned char* lds, const Gemm g, const Sched& S, const Epi& E) {
;     ...
;         cur = nxt; cA = nA; cB = nB; ++ui;
;         if constexpr (ALIGN_EPI) { if (wr == 1) PG8_BAR; }
;     __device__ __forceinline__ void operator()(const f32x4 (&acc)[2][2][4][2], const pg8::Unit& u, int wr, int wc, int fr_, int fq_, LAS const unsigned char* xl) const {
;     ...
;                 for (int m = 0; m < 4; ++m) {
;                     const int row = row0 + ai * 128 + m * 16;
;                     const float rinv = (MODE == 2) ? 1.f : rv[ai][m];
;                     if (MODE == 0 || MODE == 2) {
;                         bf16_t* rowp = O + (size_t)row * ldc + u.pn * 256 + wc * 32 + 8 * fq;
; #pragma unroll
;                         for (int bj = 0; bj < 2; ++bj) { const f32x4 v0 = acc[ai][bj][m][0] * rinv, v1 = acc[ai][bj][m][1] * rinv;
;                             u32x4 w; w.x = pg8::cvt_pk_bf16(v0[0], v0[1]); w.y = pg8::cvt_pk_bf16(v0[2], v0[3]); w.z = pg8::cvt_pk_bf16(v1[0], v1[1]); w.w = pg8::cvt_pk_bf16(v1[2], v1[3]);
;                             *(u32x4*)(rowp + bj * 128) = w; }
	v_pk_mul_f32 v[92:93], v[92:93], v[146:147] op_sel_hi:[1,0]
	v_pk_mul_f32 v[84:85], v[84:85], v[146:147] op_sel_hi:[1,0]
	v_pk_mul_f32 v[104:105], v[98:99], v[144:145] op_sel_hi:[1,0]
	v_pk_mul_f32 v[98:99], v[96:97], v[144:145] op_sel_hi:[1,0]
	v_cvt_pk_bf16_f32 v96, v100, v101
	v_cvt_pk_bf16_f32 v97, v102, v103
	v_pk_mul_f32 v[86:87], v[86:87], v[146:147] op_sel_hi:[1,0]
	v_cvt_pk_bf16_f32 v98, v98, v99
	v_cvt_pk_bf16_f32 v99, v104, v105
	global_store_dwordx4 v[112:113], v[96:99], off offset:256
	v_pk_mul_f32 v[78:79], v[78:79], v[140:141] op_sel_hi:[1,0]
	v_pk_mul_f32 v[76:77], v[76:77], v[140:141] op_sel_hi:[1,0]
	v_add_u32_e32 v96, 32, v129
	v_mad_i64_i32 v[96:97], s[24:25], v96, s83, v[130:131]
	v_lshl_add_u64 v[96:97], v[96:97], 0, s[22:23]
	v_lshl_add_u64 v[96:97], v[96:97], 0, s[86:87]
	v_lshl_add_u64 v[96:97], v[96:97], 0, v[134:135]
	v_pk_mul_f32 v[98:99], v[90:91], v[146:147] op_sel_hi:[1,0]
	v_pk_mul_f32 v[90:91], v[88:89], v[146:147] op_sel_hi:[1,0]
	v_cvt_pk_bf16_f32 v88, v92, v93
	v_cvt_pk_bf16_f32 v89, v94, v95
	v_pk_mul_f32 v[68:69], v[68:69], v[140:141] op_sel_hi:[1,0]
	v_cvt_pk_bf16_f32 v90, v90, v91
	v_cvt_pk_bf16_f32 v91, v98, v99
	global_store_dwordx4 v[96:97], v[88:91], off
	v_pk_mul_f32 v[70:71], v[70:71], v[140:141] op_sel_hi:[1,0]
	v_pk_mul_f32 v[62:63], v[62:63], v[138:139] op_sel_hi:[1,0]
	v_pk_mul_f32 v[88:89], v[82:83], v[146:147] op_sel_hi:[1,0]
	v_pk_mul_f32 v[82:83], v[80:81], v[146:147] op_sel_hi:[1,0]
	v_cvt_pk_bf16_f32 v80, v84, v85
	v_cvt_pk_bf16_f32 v81, v86, v87
	v_pk_mul_f32 v[60:61], v[60:61], v[138:139] op_sel_hi:[1,0]
	v_cvt_pk_bf16_f32 v82, v82, v83
	v_cvt_pk_bf16_f32 v83, v88, v89
	global_store_dwordx4 v[96:97], v[80:83], off offset:256
	v_pk_mul_f32 v[52:53], v[52:53], v[138:139] op_sel_hi:[1,0]
	v_pk_mul_f32 v[54:55], v[54:55], v[138:139] op_sel_hi:[1,0]
	v_add_u32_e32 v80, 48, v129
	v_mad_i64_i32 v[80:81], s[24:25], v80, s83, v[130:131]
	v_lshl_add_u64 v[80:81], v[80:81], 0, s[22:23]
	v_lshl_add_u64 v[80:81], v[80:81], 0, s[86:87]
	v_lshl_add_u64 v[80:81], v[80:81], 0, v[134:135]
	v_pk_mul_f32 v[82:83], v[74:75], v[140:141] op_sel_hi:[1,0]
	v_pk_mul_f32 v[74:75], v[72:73], v[140:141] op_sel_hi:[1,0]
	v_cvt_pk_bf16_f32 v72, v76, v77
	v_cvt_pk_bf16_f32 v73, v78, v79
	v_pk_mul_f32 v[46:47], v[46:47], v[136:137] op_sel_hi:[1,0]
	v_cvt_pk_bf16_f32 v74, v74, v75
	v_cvt_pk_bf16_f32 v75, v82, v83
	global_store_dwordx4 v[80:81], v[72:75], off
	v_pk_mul_f32 v[44:45], v[44:45], v[136:137] op_sel_hi:[1,0]
	v_pk_mul_f32 v[36:37], v[36:37], v[136:137] op_sel_hi:[1,0]
	v_pk_mul_f32 v[72:73], v[66:67], v[140:141] op_sel_hi:[1,0]
	v_pk_mul_f32 v[66:67], v[64:65], v[140:141] op_sel_hi:[1,0]
	v_cvt_pk_bf16_f32 v64, v68, v69
	v_cvt_pk_bf16_f32 v65, v70, v71
	v_pk_mul_f32 v[38:39], v[38:39], v[136:137] op_sel_hi:[1,0]
	v_cvt_pk_bf16_f32 v66, v66, v67
	v_cvt_pk_bf16_f32 v67, v72, v73
	global_store_dwordx4 v[80:81], v[64:67], off offset:256
	v_pk_mul_f32 v[30:31], v[30:31], v[132:133] op_sel_hi:[1,0]
	v_pk_mul_f32 v[28:29], v[28:29], v[132:133] op_sel_hi:[1,0]
	v_add_u32_e32 v64, 0x80, v129
	v_mad_i64_i32 v[64:65], s[24:25], v64, s83, v[130:131]
	v_lshl_add_u64 v[64:65], v[64:65], 0, s[22:23]
	v_lshl_add_u64 v[64:65], v[64:65], 0, s[86:87]
	v_lshl_add_u64 v[64:65], v[64:65], 0, v[134:135]
	v_pk_mul_f32 v[66:67], v[58:59], v[138:139] op_sel_hi:[1,0]
	v_pk_mul_f32 v[58:59], v[56:57], v[138:139] op_sel_hi:[1,0]
	v_cvt_pk_bf16_f32 v56, v60, v61
	v_cvt_pk_bf16_f32 v57, v62, v63
	v_fmamk_f32 v128, v128, 0x3a800000, v233
	v_cvt_pk_bf16_f32 v58, v58, v59
	v_cvt_pk_bf16_f32 v59, v66, v67
	global_store_dwordx4 v[64:65], v[56:59], off
	v_pk_mul_f32 v[20:21], v[20:21], v[132:133] op_sel_hi:[1,0]
	v_rsq_f32_e32 v128, v128
	v_pk_mul_f32 v[56:57], v[50:51], v[138:139] op_sel_hi:[1,0]
	v_pk_mul_f32 v[50:51], v[48:49], v[138:139] op_sel_hi:[1,0]
	v_cvt_pk_bf16_f32 v48, v52, v53
	v_cvt_pk_bf16_f32 v49, v54, v55
	v_pk_mul_f32 v[22:23], v[22:23], v[132:133] op_sel_hi:[1,0]
	v_cvt_pk_bf16_f32 v50, v50, v51
	v_cvt_pk_bf16_f32 v51, v56, v57
	global_store_dwordx4 v[64:65], v[48:51], off offset:256
	v_pk_mul_f32 v[14:15], v[14:15], v[128:129] op_sel_hi:[1,0]
	v_pk_mul_f32 v[12:13], v[12:13], v[128:129] op_sel_hi:[1,0]
	v_add_u32_e32 v48, 0x90, v129
	v_mad_i64_i32 v[48:49], s[24:25], v48, s83, v[130:131]
	v_lshl_add_u64 v[48:49], v[48:49], 0, s[22:23]
	v_lshl_add_u64 v[48:49], v[48:49], 0, s[86:87]
	v_lshl_add_u64 v[48:49], v[48:49], 0, v[134:135]
	v_pk_mul_f32 v[50:51], v[42:43], v[136:137] op_sel_hi:[1,0]
	v_pk_mul_f32 v[42:43], v[40:41], v[136:137] op_sel_hi:[1,0]
	v_cvt_pk_bf16_f32 v40, v44, v45
	v_cvt_pk_bf16_f32 v41, v46, v47
	v_pk_mul_f32 v[6:7], v[6:7], v[128:129] op_sel_hi:[1,0]
	v_cvt_pk_bf16_f32 v42, v42, v43
	v_cvt_pk_bf16_f32 v43, v50, v51
	global_store_dwordx4 v[48:49], v[40:43], off
	v_pk_mul_f32 v[4:5], v[4:5], v[128:129] op_sel_hi:[1,0]
	s_nop 0
	v_pk_mul_f32 v[40:41], v[34:35], v[136:137] op_sel_hi:[1,0]
	v_pk_mul_f32 v[34:35], v[32:33], v[136:137] op_sel_hi:[1,0]
	v_cvt_pk_bf16_f32 v32, v36, v37
	v_cvt_pk_bf16_f32 v33, v38, v39
	s_nop 0
	v_cvt_pk_bf16_f32 v34, v34, v35
	v_cvt_pk_bf16_f32 v35, v40, v41
	global_store_dwordx4 v[48:49], v[32:35], off offset:256
	s_nop 1
	v_add_u32_e32 v32, 0xa0, v129
	v_mad_i64_i32 v[32:33], s[24:25], v32, s83, v[130:131]
	v_lshl_add_u64 v[32:33], v[32:33], 0, s[22:23]
	v_lshl_add_u64 v[32:33], v[32:33], 0, s[86:87]
	v_lshl_add_u64 v[32:33], v[32:33], 0, v[134:135]
	v_pk_mul_f32 v[34:35], v[26:27], v[132:133] op_sel_hi:[1,0]
	v_pk_mul_f32 v[26:27], v[24:25], v[132:133] op_sel_hi:[1,0]
	v_cvt_pk_bf16_f32 v24, v28, v29
	v_cvt_pk_bf16_f32 v25, v30, v31
	s_nop 0
	v_cvt_pk_bf16_f32 v26, v26, v27
	v_cvt_pk_bf16_f32 v27, v34, v35
	global_store_dwordx4 v[32:33], v[24:27], off
	s_nop 1
	v_pk_mul_f32 v[24:25], v[18:19], v[132:133] op_sel_hi:[1,0]
	v_pk_mul_f32 v[18:19], v[16:17], v[132:133] op_sel_hi:[1,0]
	v_cvt_pk_bf16_f32 v16, v20, v21
	v_cvt_pk_bf16_f32 v17, v22, v23
	s_nop 0
	v_cvt_pk_bf16_f32 v18, v18, v19
	v_cvt_pk_bf16_f32 v19, v24, v25
	global_store_dwordx4 v[32:33], v[16:19], off offset:256
	s_nop 1
	v_add_u32_e32 v16, 0xb0, v129
	v_mad_i64_i32 v[16:17], s[24:25], v16, s83, v[130:131]
	v_lshl_add_u64 v[16:17], v[16:17], 0, s[22:23]
	v_lshl_add_u64 v[16:17], v[16:17], 0, s[86:87]
	v_lshl_add_u64 v[16:17], v[16:17], 0, v[134:135]
	v_pk_mul_f32 v[18:19], v[10:11], v[128:129] op_sel_hi:[1,0]
	v_pk_mul_f32 v[10:11], v[8:9], v[128:129] op_sel_hi:[1,0]
	v_cvt_pk_bf16_f32 v8, v12, v13
	v_cvt_pk_bf16_f32 v9, v14, v15
	s_mov_b64 s[22:23], -1
	v_cvt_pk_bf16_f32 v10, v10, v11
	v_cvt_pk_bf16_f32 v11, v18, v19
	global_store_dwordx4 v[16:17], v[8:11], off
	s_nop 1
	v_pk_mul_f32 v[8:9], v[2:3], v[128:129] op_sel_hi:[1,0]
	v_pk_mul_f32 v[2:3], v[0:1], v[128:129] op_sel_hi:[1,0]
	v_cvt_pk_bf16_f32 v0, v4, v5
	v_cvt_pk_bf16_f32 v1, v6, v7
	s_nop 0
	v_cvt_pk_bf16_f32 v2, v2, v3
	v_cvt_pk_bf16_f32 v3, v8, v9
	global_store_dwordx4 v[16:17], v[0:3], off offset:256
	s_cbranch_vccnz .LBB0_243
	s_andn2_b64 vcc, exec, s[0:1]
	s_cbranch_vccnz .LBB0_242
	s_barrier
	s_branch .LBB0_242

;     __host__ __device__ bool next(int i, Unit& u) const {
;         const long L = (long)i * G + c; if (L >= nwg) return false;
;         int wgid = (int)L; { const int q = nwg / NXCD, r = nwg % NXCD, xcd = wgid % NXCD, off = wgid / NXCD; wgid = (xcd < r ? xcd * (q + 1) : r * (q + 1) + (xcd - r) * q) + off; }
;         const int nig = WGM * nN, gid = wgid / nig, fm = gid * WGM, gsz = (nM - fm) < WGM ? (nM - fm) : WGM;
;         u.pm = fm + ((wgid % nig) % gsz); u.pn = (wgid % nig) / gsz; return true;
;     }
.LBB0_341:
	s_cmp_lg_u32 s88, 0x100
	s_cbranch_scc1 .Lsn_gen_1
	s_add_i32 s46, s46, 1
	s_cmp_lt_u32 s46, 4
	s_cselect_b64 s[8:9], -1, 0
	s_cbranch_scc0 .LBB0_347
	s_add_i32 s47, s2, 4
	s_mov_b32 s48, s49
	s_cmp_lt_u32 s47, 4
	s_cbranch_scc1 .LBB0_347
	s_sub_i32 s47, s47, 4
	s_add_i32 s48, s48, 8
	s_branch .LBB0_347

; __device__ __forceinline__ unsigned cvt_pk_bf16(float lo, float hi) { unsigned r; asm volatile("v_cvt_pk_bf16_f32 %0, %1, %2" : "=v"(r) : "v"(lo), "v"(hi)); return r; }
; __device__ __forceinline__ float bf_lo(unsigned w) { return __uint_as_float(w << 16); }
;     __device__ __forceinline__ void operator()(const f32x4 (&acc)[2][2][4][2], const pg8::Unit& u, int wr, int wc, int fr_, int fq_, LAS const unsigned char* xl) const {
;     ...
;                     for (int bj = 0; bj < 2; ++bj) { const size_t off = (size_t)(row0 + ai * 128 + (mb + m) * 16) * DM + col + bj * 128;
;                         hw[m][bj] = *(const u32x4*)(h_old + off); if (MODE == 4) pw[m][bj] = *(const u32x4*)(pp + off); }
; #pragma unroll
;                 for (int mm = 0; mm < MB; ++mm) {
;                     const int m = mb + mm;
;                     const int row = row0 + ai * 128 + m * 16; const float rinv = rv[ai][m];
;                     float ss = 0.f;
; #pragma unroll
;                     for (int bj = 0; bj < 2; ++bj) { const size_t off = (size_t)row * DM + col + bj * 128;
;                         const u32x4 h4 = hw[mm][bj];
;                         f32x4 a = {bf_lo(h4.x), bf_hi(h4.x), bf_lo(h4.y), bf_hi(h4.y)}, b = {bf_lo(h4.z), bf_hi(h4.z), bf_lo(h4.w), bf_hi(h4.w)};
;                         f32x4 d0 = acc[ai][bj][m][0], d1 = acc[ai][bj][m][1];
;                         if (MODE == 4) { const u32x4 p4 = pw[mm][bj];
;                             d0[0] = fast_sigmoid(d0[0] * rinv) * bf_lo(p4.x); d0[1] = fast_sigmoid(d0[1] * rinv) * bf_hi(p4.x);
;                             d0[2] = fast_sigmoid(d0[2] * rinv) * bf_lo(p4.y); d0[3] = fast_sigmoid(d0[3] * rinv) * bf_hi(p4.y);
;                             d1[0] = fast_sigmoid(d1[0] * rinv) * bf_lo(p4.z); d1[1] = fast_sigmoid(d1[1] * rinv) * bf_hi(p4.z);
;                             d1[2] = fast_sigmoid(d1[2] * rinv) * bf_lo(p4.w); d1[3] = fast_sigmoid(d1[3] * rinv) * bf_hi(p4.w); }
;                         a += d0; b += d1;
;                         u32x4 w; w.x = pg8::cvt_pk_bf16(a[0], a[1]); w.y = pg8::cvt_pk_bf16(a[2], a[3]); w.z = pg8::cvt_pk_bf16(b[0], b[1]); w.w = pg8::cvt_pk_bf16(b[2], b[3]);
;                         *(u32x4*)(O + off) = w;
;                         ss += (a[0] * a[0] + a[1] * a[1]) + (a[2] * a[2] + a[3] * a[3]) + (b[0] * b[0] + b[1] * b[1]) + (b[2] * b[2] + b[3] * b[3]); }
.LBB0_356:
	s_lshl_b32 s0, s49, 8
	s_add_i32 s0, s0, s41
	v_readlane_b32 s28, v255, 24
	v_readlane_b32 s29, v255, 25
	v_add_u32_e32 v200, s0, v184
	s_lshl_b32 s0, s2, 8
	s_or_b32 s0, s0, s42
	v_lshl_add_u32 v201, v185, 3, s0
	v_lshlrev_b32_e32 v202, 11, v200
	v_lshl_or_b32 v202, v201, 1, v202
	v_mov_b32_e32 v203, 0
	s_mov_b32 s100, 0x8000
	s_mov_b32 s101, 0
	s_lshl_b32 s0, s2, 4
	s_lshl_b32 s86, s39, 2
	s_add_i32 s86, s86, s0
	s_mov_b32 s0, 0x28000
	s_mov_b32 s1, 0
	v_lshl_add_u64 v[194:195], s[28:29], 0, v[202:203]
	global_load_dwordx4 v[128:131], v[194:195], off
	global_load_dwordx4 v[132:135], v[194:195], off offset:256
	v_lshl_add_u64 v[166:167], v[194:195], 0, s[100:101]
	global_load_dwordx4 v[136:139], v[166:167], off
	global_load_dwordx4 v[140:143], v[166:167], off offset:256
	v_lshl_add_u64 v[194:195], v[166:167], 0, s[100:101]
	global_load_dwordx4 v[144:147], v[194:195], off
	global_load_dwordx4 v[148:151], v[194:195], off offset:256
	v_lshl_add_u64 v[166:167], v[194:195], 0, s[100:101]
	global_load_dwordx4 v[152:155], v[166:167], off
	global_load_dwordx4 v[168:171], v[166:167], off offset:256
	v_lshl_add_u64 v[194:195], v[166:167], 0, s[0:1]
	global_load_dwordx4 v[172:175], v[194:195], off
	global_load_dwordx4 v[176:179], v[194:195], off offset:256
	v_lshl_add_u64 v[166:167], v[194:195], 0, s[100:101]
	global_load_dwordx4 v[180:183], v[166:167], off
	global_load_dwordx4 v[188:191], v[166:167], off offset:256
	v_lshl_add_u64 v[194:195], v[166:167], 0, s[100:101]
	global_load_dwordx4 v[204:207], v[194:195], off
	global_load_dwordx4 v[208:211], v[194:195], off offset:256
	v_lshl_add_u64 v[166:167], v[194:195], 0, s[100:101]
	v_lshlrev_b32_e32 v200, 6, v200
	v_add_u32_e32 v200, s86, v200
	v_mov_b32_e32 v201, 0
	v_lshl_add_u64 v[200:201], s[10:11], 0, v[200:201]
	v_lshl_add_u64 v[194:195], s[28:29], 0, v[202:203]
	s_waitcnt vmcnt(12)
	v_lshlrev_b32_e32 v212, 16, v128
	v_lshlrev_b32_e32 v213, 16, v129
	v_lshlrev_b32_e32 v214, 16, v130
	v_lshlrev_b32_e32 v215, 16, v131
	v_lshlrev_b32_e32 v216, 16, v132
	v_lshlrev_b32_e32 v217, 16, v133
	v_lshlrev_b32_e32 v218, 16, v134
	v_lshlrev_b32_e32 v219, 16, v135
	v_and_b32_e32 v128, 0xffff0000, v128
	v_and_b32_e32 v129, 0xffff0000, v129
	v_and_b32_e32 v130, 0xffff0000, v130
	v_and_b32_e32 v131, 0xffff0000, v131
	v_and_b32_e32 v132, 0xffff0000, v132
	v_and_b32_e32 v133, 0xffff0000, v133
	v_and_b32_e32 v134, 0xffff0000, v134
	v_and_b32_e32 v135, 0xffff0000, v135
	v_add_f32_e32 v120, v120, v212
	v_add_f32_e32 v121, v121, v128
	v_add_f32_e32 v122, v122, v213
	v_add_f32_e32 v123, v123, v129
	v_add_f32_e32 v124, v124, v214
	v_add_f32_e32 v125, v125, v130
	v_add_f32_e32 v126, v126, v215
	v_add_f32_e32 v127, v127, v131
	v_add_f32_e32 v116, v116, v216
	v_add_f32_e32 v117, v117, v132
	v_add_f32_e32 v118, v118, v217
	v_add_f32_e32 v119, v119, v133
	v_add_f32_e32 v112, v112, v218
	v_add_f32_e32 v113, v113, v134
	v_add_f32_e32 v114, v114, v219
	v_add_f32_e32 v115, v115, v135
	v_mul_f32_e32 v212, v120, v120
	v_mul_f32_e32 v213, v124, v124
	v_mul_f32_e32 v214, v116, v116
	v_mul_f32_e32 v215, v112, v112
	v_fmac_f32_e32 v212, v121, v121
	v_fmac_f32_e32 v213, v125, v125
	v_fmac_f32_e32 v214, v117, v117
	v_fmac_f32_e32 v215, v113, v113
	v_fmac_f32_e32 v212, v122, v122
	v_fmac_f32_e32 v213, v126, v126
	v_fmac_f32_e32 v214, v118, v118
	v_fmac_f32_e32 v215, v114, v114
	v_fmac_f32_e32 v212, v123, v123
	v_fmac_f32_e32 v213, v127, v127
	v_fmac_f32_e32 v214, v119, v119
	v_fmac_f32_e32 v215, v115, v115
	v_cvt_pk_bf16_f32 v120, v120, v121
	v_cvt_pk_bf16_f32 v121, v122, v123
	v_cvt_pk_bf16_f32 v122, v124, v125
	v_cvt_pk_bf16_f32 v123, v126, v127
	v_cvt_pk_bf16_f32 v116, v116, v117
	v_cvt_pk_bf16_f32 v117, v118, v119
	v_cvt_pk_bf16_f32 v118, v112, v113
	v_cvt_pk_bf16_f32 v119, v114, v115
	global_store_dwordx4 v[194:195], v[120:123], off
	global_store_dwordx4 v[194:195], v[116:119], off offset:256
	v_add_f32_e32 v212, v212, v213
	v_add_f32_e32 v214, v214, v215
	v_add_f32_e32 v124, v212, v214
	global_load_dwordx4 v[212:215], v[166:167], off
	global_load_dwordx4 v[216:219], v[166:167], off offset:256
	v_lshl_add_u64 v[166:167], v[194:195], 0, s[100:101]
	s_waitcnt vmcnt(14)
	v_lshlrev_b32_e32 v128, 16, v136
	v_lshlrev_b32_e32 v129, 16, v137
	v_lshlrev_b32_e32 v130, 16, v138
	v_lshlrev_b32_e32 v131, 16, v139
	v_lshlrev_b32_e32 v132, 16, v140
	v_lshlrev_b32_e32 v133, 16, v141
	v_lshlrev_b32_e32 v134, 16, v142
	v_lshlrev_b32_e32 v135, 16, v143
	v_and_b32_e32 v136, 0xffff0000, v136
	v_and_b32_e32 v137, 0xffff0000, v137
	v_and_b32_e32 v138, 0xffff0000, v138
	v_and_b32_e32 v139, 0xffff0000, v139
	v_and_b32_e32 v140, 0xffff0000, v140
	v_and_b32_e32 v141, 0xffff0000, v141
	v_and_b32_e32 v142, 0xffff0000, v142
	v_and_b32_e32 v143, 0xffff0000, v143
	v_add_f32_e32 v108, v108, v128
	v_add_f32_e32 v109, v109, v136
	v_add_f32_e32 v110, v110, v129
	v_add_f32_e32 v111, v111, v137
	v_add_f32_e32 v104, v104, v130
	v_add_f32_e32 v105, v105, v138
	v_add_f32_e32 v106, v106, v131
	v_add_f32_e32 v107, v107, v139
	v_add_f32_e32 v100, v100, v132
	v_add_f32_e32 v101, v101, v140
	v_add_f32_e32 v102, v102, v133
	v_add_f32_e32 v103, v103, v141
	v_add_f32_e32 v96, v96, v134
	v_add_f32_e32 v97, v97, v142
	v_add_f32_e32 v98, v98, v135
	v_add_f32_e32 v99, v99, v143
	v_mul_f32_e32 v128, v108, v108
	v_mul_f32_e32 v129, v104, v104
	v_mul_f32_e32 v130, v100, v100
	v_mul_f32_e32 v131, v96, v96
	v_fmac_f32_e32 v128, v109, v109
	v_fmac_f32_e32 v129, v105, v105
	v_fmac_f32_e32 v130, v101, v101
	v_fmac_f32_e32 v131, v97, v97
	v_fmac_f32_e32 v128, v110, v110
	v_fmac_f32_e32 v129, v106, v106
	v_fmac_f32_e32 v130, v102, v102
	v_fmac_f32_e32 v131, v98, v98
	v_fmac_f32_e32 v128, v111, v111
	v_fmac_f32_e32 v129, v107, v107
	v_fmac_f32_e32 v130, v103, v103
	v_fmac_f32_e32 v131, v99, v99
	v_cvt_pk_bf16_f32 v108, v108, v109
	v_cvt_pk_bf16_f32 v109, v110, v111
	v_cvt_pk_bf16_f32 v110, v104, v105
	v_cvt_pk_bf16_f32 v111, v106, v107
	v_cvt_pk_bf16_f32 v100, v100, v101
	v_cvt_pk_bf16_f32 v101, v102, v103
	v_cvt_pk_bf16_f32 v102, v96, v97
	v_cvt_pk_bf16_f32 v103, v98, v99
	global_store_dwordx4 v[166:167], v[108:111], off
	global_store_dwordx4 v[166:167], v[100:103], off offset:256
	v_add_f32_e32 v128, v128, v129
	v_add_f32_e32 v130, v130, v131
	v_add_f32_e32 v104, v128, v130
	v_lshl_add_u64 v[194:195], v[166:167], 0, s[100:101]
	s_waitcnt vmcnt(14)
; __device__ __forceinline__ unsigned cvt_pk_bf16(float lo, float hi) { unsigned r; asm volatile("v_cvt_pk_bf16_f32 %0, %1, %2" : "=v"(r) : "v"(lo), "v"(hi)); return r; }
; __device__ __forceinline__ float bf_lo(unsigned w) { return __uint_as_float(w << 16); }
; __device__ __forceinline__ float bf_hi(unsigned w) { return __uint_as_float(w & 0xffff0000u); }
; __device__ __forceinline__ float fast_sigmoid(float x) { return __builtin_amdgcn_rcpf(1.0f + __expf(-x)); }
;     __device__ __forceinline__ void operator()(const f32x4 (&acc)[2][2][4][2], const pg8::Unit& u, int wr, int wc, int fr_, int fq_, LAS const unsigned char* xl) const {
;     ...
;                     for (int bj = 0; bj < 2; ++bj) { const size_t off = (size_t)row * DM + col + bj * 128;
;                         const u32x4 h4 = hw[mm][bj];
;                         f32x4 a = {bf_lo(h4.x), bf_hi(h4.x), bf_lo(h4.y), bf_hi(h4.y)}, b = {bf_lo(h4.z), bf_hi(h4.z), bf_lo(h4.w), bf_hi(h4.w)};
;                         f32x4 d0 = acc[ai][bj][m][0], d1 = acc[ai][bj][m][1];
;                         if (MODE == 4) { const u32x4 p4 = pw[mm][bj];
;                             d0[0] = fast_sigmoid(d0[0] * rinv) * bf_lo(p4.x); d0[1] = fast_sigmoid(d0[1] * rinv) * bf_hi(p4.x);
;                             d0[2] = fast_sigmoid(d0[2] * rinv) * bf_lo(p4.y); d0[3] = fast_sigmoid(d0[3] * rinv) * bf_hi(p4.y);
;                             d1[0] = fast_sigmoid(d1[0] * rinv) * bf_lo(p4.z); d1[1] = fast_sigmoid(d1[1] * rinv) * bf_hi(p4.z);
;                             d1[2] = fast_sigmoid(d1[2] * rinv) * bf_lo(p4.w); d1[3] = fast_sigmoid(d1[3] * rinv) * bf_hi(p4.w); }
;                         a += d0; b += d1;
;                         u32x4 w; w.x = pg8::cvt_pk_bf16(a[0], a[1]); w.y = pg8::cvt_pk_bf16(a[2], a[3]); w.z = pg8::cvt_pk_bf16(b[0], b[1]); w.w = pg8::cvt_pk_bf16(b[2], b[3]);
;                         *(u32x4*)(O + off) = w;
;                         ss += (a[0] * a[0] + a[1] * a[1]) + (a[2] * a[2] + a[3] * a[3]) + (b[0] * b[0] + b[1] * b[1]) + (b[2] * b[2] + b[3] * b[3]); }
	v_lshlrev_b32_e32 v136, 16, v144
	v_lshlrev_b32_e32 v137, 16, v145
	v_lshlrev_b32_e32 v138, 16, v146
	v_lshlrev_b32_e32 v139, 16, v147
	v_lshlrev_b32_e32 v140, 16, v148
	v_lshlrev_b32_e32 v141, 16, v149
	v_lshlrev_b32_e32 v142, 16, v150
	v_lshlrev_b32_e32 v143, 16, v151
	v_and_b32_e32 v144, 0xffff0000, v144
	v_and_b32_e32 v145, 0xffff0000, v145
	v_and_b32_e32 v146, 0xffff0000, v146
	v_and_b32_e32 v147, 0xffff0000, v147
	v_and_b32_e32 v148, 0xffff0000, v148
	v_and_b32_e32 v149, 0xffff0000, v149
	v_and_b32_e32 v150, 0xffff0000, v150
	v_and_b32_e32 v151, 0xffff0000, v151
	v_add_f32_e32 v92, v92, v136
	v_add_f32_e32 v93, v93, v144
	v_add_f32_e32 v94, v94, v137
	v_add_f32_e32 v95, v95, v145
	v_add_f32_e32 v88, v88, v138
	v_add_f32_e32 v89, v89, v146
	v_add_f32_e32 v90, v90, v139
	v_add_f32_e32 v91, v91, v147
	v_add_f32_e32 v84, v84, v140
	v_add_f32_e32 v85, v85, v148
	v_add_f32_e32 v86, v86, v141
	v_add_f32_e32 v87, v87, v149
	v_add_f32_e32 v80, v80, v142
	v_add_f32_e32 v81, v81, v150
	v_add_f32_e32 v82, v82, v143
	v_add_f32_e32 v83, v83, v151
	v_mul_f32_e32 v136, v92, v92
	v_mul_f32_e32 v137, v88, v88
	v_mul_f32_e32 v138, v84, v84
	v_mul_f32_e32 v139, v80, v80
	v_fmac_f32_e32 v136, v93, v93
	v_fmac_f32_e32 v137, v89, v89
	v_fmac_f32_e32 v138, v85, v85
	v_fmac_f32_e32 v139, v81, v81
	v_fmac_f32_e32 v136, v94, v94
	v_fmac_f32_e32 v137, v90, v90
	v_fmac_f32_e32 v138, v86, v86
	v_fmac_f32_e32 v139, v82, v82
	v_fmac_f32_e32 v136, v95, v95
	v_fmac_f32_e32 v137, v91, v91
	v_fmac_f32_e32 v138, v87, v87
	v_fmac_f32_e32 v139, v83, v83
	v_cvt_pk_bf16_f32 v92, v92, v93
	v_cvt_pk_bf16_f32 v93, v94, v95
	v_cvt_pk_bf16_f32 v94, v88, v89
	v_cvt_pk_bf16_f32 v95, v90, v91
	v_cvt_pk_bf16_f32 v84, v84, v85
	v_cvt_pk_bf16_f32 v85, v86, v87
	v_cvt_pk_bf16_f32 v86, v80, v81
	v_cvt_pk_bf16_f32 v87, v82, v83
	global_store_dwordx4 v[194:195], v[92:95], off
	global_store_dwordx4 v[194:195], v[84:87], off offset:256
	v_add_f32_e32 v136, v136, v137
	v_add_f32_e32 v138, v138, v139
	v_add_f32_e32 v88, v136, v138
	v_lshl_add_u64 v[166:167], v[194:195], 0, s[100:101]
	s_waitcnt vmcnt(14)
	v_lshlrev_b32_e32 v144, 16, v152
	v_lshlrev_b32_e32 v145, 16, v153
	v_lshlrev_b32_e32 v146, 16, v154
	v_lshlrev_b32_e32 v147, 16, v155
	v_lshlrev_b32_e32 v148, 16, v168
	v_lshlrev_b32_e32 v149, 16, v169
	v_lshlrev_b32_e32 v150, 16, v170
	v_lshlrev_b32_e32 v151, 16, v171
	v_and_b32_e32 v152, 0xffff0000, v152
	v_and_b32_e32 v153, 0xffff0000, v153
	v_and_b32_e32 v154, 0xffff0000, v154
	v_and_b32_e32 v155, 0xffff0000, v155
	v_and_b32_e32 v168, 0xffff0000, v168
	v_and_b32_e32 v169, 0xffff0000, v169
	v_and_b32_e32 v170, 0xffff0000, v170
	v_and_b32_e32 v171, 0xffff0000, v171
	v_add_f32_e32 v76, v76, v144
	v_add_f32_e32 v77, v77, v152
	v_add_f32_e32 v78, v78, v145
	v_add_f32_e32 v79, v79, v153
	v_add_f32_e32 v72, v72, v146
	v_add_f32_e32 v73, v73, v154
	v_add_f32_e32 v74, v74, v147
	v_add_f32_e32 v75, v75, v155
	v_add_f32_e32 v68, v68, v148
	v_add_f32_e32 v69, v69, v168
	v_add_f32_e32 v70, v70, v149
	v_add_f32_e32 v71, v71, v169
	v_add_f32_e32 v64, v64, v150
	v_add_f32_e32 v65, v65, v170
	v_add_f32_e32 v66, v66, v151
	v_add_f32_e32 v67, v67, v171
	v_mul_f32_e32 v144, v76, v76
	v_mul_f32_e32 v145, v72, v72
	v_mul_f32_e32 v146, v68, v68
	v_mul_f32_e32 v147, v64, v64
	v_fmac_f32_e32 v144, v77, v77
	v_fmac_f32_e32 v145, v73, v73
	v_fmac_f32_e32 v146, v69, v69
	v_fmac_f32_e32 v147, v65, v65
	v_fmac_f32_e32 v144, v78, v78
	v_fmac_f32_e32 v145, v74, v74
	v_fmac_f32_e32 v146, v70, v70
	v_fmac_f32_e32 v147, v66, v66
	v_fmac_f32_e32 v144, v79, v79
	v_fmac_f32_e32 v145, v75, v75
	v_fmac_f32_e32 v146, v71, v71
	v_fmac_f32_e32 v147, v67, v67
	v_cvt_pk_bf16_f32 v76, v76, v77
	v_cvt_pk_bf16_f32 v77, v78, v79
	v_cvt_pk_bf16_f32 v78, v72, v73
	v_cvt_pk_bf16_f32 v79, v74, v75
	v_cvt_pk_bf16_f32 v68, v68, v69
	v_cvt_pk_bf16_f32 v69, v70, v71
	v_cvt_pk_bf16_f32 v70, v64, v65
	v_cvt_pk_bf16_f32 v71, v66, v67
	global_store_dwordx4 v[166:167], v[76:79], off
	global_store_dwordx4 v[166:167], v[68:71], off offset:256
	v_add_f32_e32 v144, v144, v145
	v_add_f32_e32 v146, v146, v147
	v_add_f32_e32 v72, v144, v146
	v_lshl_add_u64 v[194:195], v[166:167], 0, s[0:1]
	s_waitcnt vmcnt(14)
	v_lshlrev_b32_e32 v152, 16, v172
	v_lshlrev_b32_e32 v153, 16, v173
	v_lshlrev_b32_e32 v154, 16, v174
	v_lshlrev_b32_e32 v155, 16, v175
	v_lshlrev_b32_e32 v168, 16, v176
	v_lshlrev_b32_e32 v169, 16, v177
	v_lshlrev_b32_e32 v170, 16, v178
	v_lshlrev_b32_e32 v171, 16, v179
	v_and_b32_e32 v172, 0xffff0000, v172
	v_and_b32_e32 v173, 0xffff0000, v173
	v_and_b32_e32 v174, 0xffff0000, v174
	v_and_b32_e32 v175, 0xffff0000, v175
	v_and_b32_e32 v176, 0xffff0000, v176
	v_and_b32_e32 v177, 0xffff0000, v177
	v_and_b32_e32 v178, 0xffff0000, v178
	v_and_b32_e32 v179, 0xffff0000, v179
	v_add_f32_e32 v60, v60, v152
	v_add_f32_e32 v61, v61, v172
	v_add_f32_e32 v62, v62, v153
	v_add_f32_e32 v63, v63, v173
	v_add_f32_e32 v56, v56, v154
	v_add_f32_e32 v57, v57, v174
	v_add_f32_e32 v58, v58, v155
	v_add_f32_e32 v59, v59, v175
	v_add_f32_e32 v52, v52, v168
	v_add_f32_e32 v53, v53, v176
	v_add_f32_e32 v54, v54, v169
	v_add_f32_e32 v55, v55, v177
	v_add_f32_e32 v48, v48, v170
	v_add_f32_e32 v49, v49, v178
	v_add_f32_e32 v50, v50, v171
	v_add_f32_e32 v51, v51, v179
	v_mul_f32_e32 v152, v60, v60
	v_mul_f32_e32 v153, v56, v56
	v_mul_f32_e32 v154, v52, v52
	v_mul_f32_e32 v155, v48, v48
	v_fmac_f32_e32 v152, v61, v61
	v_fmac_f32_e32 v153, v57, v57
	v_fmac_f32_e32 v154, v53, v53
	v_fmac_f32_e32 v155, v49, v49
	v_fmac_f32_e32 v152, v62, v62
	v_fmac_f32_e32 v153, v58, v58
	v_fmac_f32_e32 v154, v54, v54
	v_fmac_f32_e32 v155, v50, v50
	v_fmac_f32_e32 v152, v63, v63
	v_fmac_f32_e32 v153, v59, v59
	v_fmac_f32_e32 v154, v55, v55
	v_fmac_f32_e32 v155, v51, v51
	v_cvt_pk_bf16_f32 v60, v60, v61
	v_cvt_pk_bf16_f32 v61, v62, v63
	v_cvt_pk_bf16_f32 v62, v56, v57
	v_cvt_pk_bf16_f32 v63, v58, v59
	v_cvt_pk_bf16_f32 v52, v52, v53
	v_cvt_pk_bf16_f32 v53, v54, v55
	v_cvt_pk_bf16_f32 v54, v48, v49
	v_cvt_pk_bf16_f32 v55, v50, v51
	global_store_dwordx4 v[194:195], v[60:63], off
	global_store_dwordx4 v[194:195], v[52:55], off offset:256
	v_add_f32_e32 v152, v152, v153
	v_add_f32_e32 v154, v154, v155
	v_add_f32_e32 v56, v152, v154
	v_lshl_add_u64 v[166:167], v[194:195], 0, s[100:101]
	s_waitcnt vmcnt(14)
; __device__ __forceinline__ unsigned cvt_pk_bf16(float lo, float hi) { unsigned r; asm volatile("v_cvt_pk_bf16_f32 %0, %1, %2" : "=v"(r) : "v"(lo), "v"(hi)); return r; }
; __device__ __forceinline__ float bf_lo(unsigned w) { return __uint_as_float(w << 16); }
; __device__ __forceinline__ float bf_hi(unsigned w) { return __uint_as_float(w & 0xffff0000u); }
; __device__ __forceinline__ float fast_sigmoid(float x) { return __builtin_amdgcn_rcpf(1.0f + __expf(-x)); }
;     __device__ __forceinline__ void operator()(const f32x4 (&acc)[2][2][4][2], const pg8::Unit& u, int wr, int wc, int fr_, int fq_, LAS const unsigned char* xl) const {
;     ...
;                     for (int bj = 0; bj < 2; ++bj) { const size_t off = (size_t)row * DM + col + bj * 128;
;                         const u32x4 h4 = hw[mm][bj];
;                         f32x4 a = {bf_lo(h4.x), bf_hi(h4.x), bf_lo(h4.y), bf_hi(h4.y)}, b = {bf_lo(h4.z), bf_hi(h4.z), bf_lo(h4.w), bf_hi(h4.w)};
;                         f32x4 d0 = acc[ai][bj][m][0], d1 = acc[ai][bj][m][1];
;                         if (MODE == 4) { const u32x4 p4 = pw[mm][bj];
;                             d0[0] = fast_sigmoid(d0[0] * rinv) * bf_lo(p4.x); d0[1] = fast_sigmoid(d0[1] * rinv) * bf_hi(p4.x);
;                             d0[2] = fast_sigmoid(d0[2] * rinv) * bf_lo(p4.y); d0[3] = fast_sigmoid(d0[3] * rinv) * bf_hi(p4.y);
;                             d1[0] = fast_sigmoid(d1[0] * rinv) * bf_lo(p4.z); d1[1] = fast_sigmoid(d1[1] * rinv) * bf_hi(p4.z);
;                             d1[2] = fast_sigmoid(d1[2] * rinv) * bf_lo(p4.w); d1[3] = fast_sigmoid(d1[3] * rinv) * bf_hi(p4.w); }
;                         a += d0; b += d1;
;                         u32x4 w; w.x = pg8::cvt_pk_bf16(a[0], a[1]); w.y = pg8::cvt_pk_bf16(a[2], a[3]); w.z = pg8::cvt_pk_bf16(b[0], b[1]); w.w = pg8::cvt_pk_bf16(b[2], b[3]);
;                         *(u32x4*)(O + off) = w;
;                         ss += (a[0] * a[0] + a[1] * a[1]) + (a[2] * a[2] + a[3] * a[3]) + (b[0] * b[0] + b[1] * b[1]) + (b[2] * b[2] + b[3] * b[3]); }
	v_lshlrev_b32_e32 v172, 16, v180
	v_lshlrev_b32_e32 v173, 16, v181
	v_lshlrev_b32_e32 v174, 16, v182
	v_lshlrev_b32_e32 v175, 16, v183
	v_lshlrev_b32_e32 v176, 16, v188
	v_lshlrev_b32_e32 v177, 16, v189
	v_lshlrev_b32_e32 v178, 16, v190
	v_lshlrev_b32_e32 v179, 16, v191
	v_and_b32_e32 v180, 0xffff0000, v180
	v_and_b32_e32 v181, 0xffff0000, v181
	v_and_b32_e32 v182, 0xffff0000, v182
	v_and_b32_e32 v183, 0xffff0000, v183
	v_and_b32_e32 v188, 0xffff0000, v188
	v_and_b32_e32 v189, 0xffff0000, v189
	v_and_b32_e32 v190, 0xffff0000, v190
	v_and_b32_e32 v191, 0xffff0000, v191
	v_add_f32_e32 v44, v44, v172
	v_add_f32_e32 v45, v45, v180
	v_add_f32_e32 v46, v46, v173
	v_add_f32_e32 v47, v47, v181
	v_add_f32_e32 v40, v40, v174
	v_add_f32_e32 v41, v41, v182
	v_add_f32_e32 v42, v42, v175
	v_add_f32_e32 v43, v43, v183
	v_add_f32_e32 v36, v36, v176
	v_add_f32_e32 v37, v37, v188
	v_add_f32_e32 v38, v38, v177
	v_add_f32_e32 v39, v39, v189
	v_add_f32_e32 v32, v32, v178
	v_add_f32_e32 v33, v33, v190
	v_add_f32_e32 v34, v34, v179
	v_add_f32_e32 v35, v35, v191
	v_mul_f32_e32 v172, v44, v44
	v_mul_f32_e32 v173, v40, v40
	v_mul_f32_e32 v174, v36, v36
	v_mul_f32_e32 v175, v32, v32
	v_fmac_f32_e32 v172, v45, v45
	v_fmac_f32_e32 v173, v41, v41
	v_fmac_f32_e32 v174, v37, v37
	v_fmac_f32_e32 v175, v33, v33
	v_fmac_f32_e32 v172, v46, v46
	v_fmac_f32_e32 v173, v42, v42
	v_fmac_f32_e32 v174, v38, v38
	v_fmac_f32_e32 v175, v34, v34
	v_fmac_f32_e32 v172, v47, v47
	v_fmac_f32_e32 v173, v43, v43
	v_fmac_f32_e32 v174, v39, v39
	v_fmac_f32_e32 v175, v35, v35
	v_cvt_pk_bf16_f32 v44, v44, v45
	v_cvt_pk_bf16_f32 v45, v46, v47
	v_cvt_pk_bf16_f32 v46, v40, v41
	v_cvt_pk_bf16_f32 v47, v42, v43
	v_cvt_pk_bf16_f32 v36, v36, v37
	v_cvt_pk_bf16_f32 v37, v38, v39
	v_cvt_pk_bf16_f32 v38, v32, v33
	v_cvt_pk_bf16_f32 v39, v34, v35
	global_store_dwordx4 v[166:167], v[44:47], off
	global_store_dwordx4 v[166:167], v[36:39], off offset:256
	v_add_f32_e32 v172, v172, v173
	v_add_f32_e32 v174, v174, v175
	v_add_f32_e32 v40, v172, v174
	v_lshl_add_u64 v[194:195], v[166:167], 0, s[100:101]
	s_waitcnt vmcnt(14)
	v_lshlrev_b32_e32 v180, 16, v204
	v_lshlrev_b32_e32 v181, 16, v205
	v_lshlrev_b32_e32 v182, 16, v206
	v_lshlrev_b32_e32 v183, 16, v207
	v_lshlrev_b32_e32 v188, 16, v208
	v_lshlrev_b32_e32 v189, 16, v209
	v_lshlrev_b32_e32 v190, 16, v210
	v_lshlrev_b32_e32 v191, 16, v211
	v_and_b32_e32 v204, 0xffff0000, v204
	v_and_b32_e32 v205, 0xffff0000, v205
	v_and_b32_e32 v206, 0xffff0000, v206
	v_and_b32_e32 v207, 0xffff0000, v207
	v_and_b32_e32 v208, 0xffff0000, v208
	v_and_b32_e32 v209, 0xffff0000, v209
	v_and_b32_e32 v210, 0xffff0000, v210
	v_and_b32_e32 v211, 0xffff0000, v211
	v_add_f32_e32 v28, v28, v180
	v_add_f32_e32 v29, v29, v204
	v_add_f32_e32 v30, v30, v181
	v_add_f32_e32 v31, v31, v205
	v_add_f32_e32 v24, v24, v182
	v_add_f32_e32 v25, v25, v206
	v_add_f32_e32 v26, v26, v183
	v_add_f32_e32 v27, v27, v207
	v_add_f32_e32 v20, v20, v188
	v_add_f32_e32 v21, v21, v208
	v_add_f32_e32 v22, v22, v189
	v_add_f32_e32 v23, v23, v209
	v_add_f32_e32 v16, v16, v190
	v_add_f32_e32 v17, v17, v210
	v_add_f32_e32 v18, v18, v191
	v_add_f32_e32 v19, v19, v211
	v_mul_f32_e32 v180, v28, v28
	v_mul_f32_e32 v181, v24, v24
	v_mul_f32_e32 v182, v20, v20
	v_mul_f32_e32 v183, v16, v16
	v_fmac_f32_e32 v180, v29, v29
	v_fmac_f32_e32 v181, v25, v25
	v_fmac_f32_e32 v182, v21, v21
	v_fmac_f32_e32 v183, v17, v17
	v_fmac_f32_e32 v180, v30, v30
	v_fmac_f32_e32 v181, v26, v26
	v_fmac_f32_e32 v182, v22, v22
	v_fmac_f32_e32 v183, v18, v18
	v_fmac_f32_e32 v180, v31, v31
	v_fmac_f32_e32 v181, v27, v27
	v_fmac_f32_e32 v182, v23, v23
	v_fmac_f32_e32 v183, v19, v19
	v_cvt_pk_bf16_f32 v28, v28, v29
	v_cvt_pk_bf16_f32 v29, v30, v31
	v_cvt_pk_bf16_f32 v30, v24, v25
	v_cvt_pk_bf16_f32 v31, v26, v27
	v_cvt_pk_bf16_f32 v20, v20, v21
	v_cvt_pk_bf16_f32 v21, v22, v23
	v_cvt_pk_bf16_f32 v22, v16, v17
	v_cvt_pk_bf16_f32 v23, v18, v19
	global_store_dwordx4 v[194:195], v[28:31], off
	global_store_dwordx4 v[194:195], v[20:23], off offset:256
	v_add_f32_e32 v180, v180, v181
	v_add_f32_e32 v182, v182, v183
	v_add_f32_e32 v24, v180, v182
	v_lshl_add_u64 v[166:167], v[194:195], 0, s[100:101]
	s_waitcnt vmcnt(12)
; __device__ __forceinline__ unsigned cvt_pk_bf16(float lo, float hi) { unsigned r; asm volatile("v_cvt_pk_bf16_f32 %0, %1, %2" : "=v"(r) : "v"(lo), "v"(hi)); return r; }
; __device__ __forceinline__ float bf_lo(unsigned w) { return __uint_as_float(w << 16); }
; __device__ __forceinline__ float bf_hi(unsigned w) { return __uint_as_float(w & 0xffff0000u); }
; __device__ __forceinline__ float fast_sigmoid(float x) { return __builtin_amdgcn_rcpf(1.0f + __expf(-x)); }
;     __device__ __forceinline__ void operator()(const f32x4 (&acc)[2][2][4][2], const pg8::Unit& u, int wr, int wc, int fr_, int fq_, LAS const unsigned char* xl) const {
;     ...
;                     for (int bj = 0; bj < 2; ++bj) { const size_t off = (size_t)row * DM + col + bj * 128;
;                         const u32x4 h4 = hw[mm][bj];
;                         f32x4 a = {bf_lo(h4.x), bf_hi(h4.x), bf_lo(h4.y), bf_hi(h4.y)}, b = {bf_lo(h4.z), bf_hi(h4.z), bf_lo(h4.w), bf_hi(h4.w)};
;                         f32x4 d0 = acc[ai][bj][m][0], d1 = acc[ai][bj][m][1];
;                         if (MODE == 4) { const u32x4 p4 = pw[mm][bj];
;                             d0[0] = fast_sigmoid(d0[0] * rinv) * bf_lo(p4.x); d0[1] = fast_sigmoid(d0[1] * rinv) * bf_hi(p4.x);
;                             d0[2] = fast_sigmoid(d0[2] * rinv) * bf_lo(p4.y); d0[3] = fast_sigmoid(d0[3] * rinv) * bf_hi(p4.y);
;                             d1[0] = fast_sigmoid(d1[0] * rinv) * bf_lo(p4.z); d1[1] = fast_sigmoid(d1[1] * rinv) * bf_hi(p4.z);
;                             d1[2] = fast_sigmoid(d1[2] * rinv) * bf_lo(p4.w); d1[3] = fast_sigmoid(d1[3] * rinv) * bf_hi(p4.w); }
;                         a += d0; b += d1;
;                         u32x4 w; w.x = pg8::cvt_pk_bf16(a[0], a[1]); w.y = pg8::cvt_pk_bf16(a[2], a[3]); w.z = pg8::cvt_pk_bf16(b[0], b[1]); w.w = pg8::cvt_pk_bf16(b[2], b[3]);
;                         *(u32x4*)(O + off) = w;
;                         ss += (a[0] * a[0] + a[1] * a[1]) + (a[2] * a[2] + a[3] * a[3]) + (b[0] * b[0] + b[1] * b[1]) + (b[2] * b[2] + b[3] * b[3]); }
;                     ss = xrow16_sum(ss);
;                     if (fq == 0) part_out[(size_t)row * 16 + u.pn * 4 + wc] = ss;
	v_lshlrev_b32_e32 v204, 16, v212
	v_lshlrev_b32_e32 v205, 16, v213
	v_lshlrev_b32_e32 v206, 16, v214
	v_lshlrev_b32_e32 v207, 16, v215
	v_lshlrev_b32_e32 v208, 16, v216
	v_lshlrev_b32_e32 v209, 16, v217
	v_lshlrev_b32_e32 v210, 16, v218
	v_lshlrev_b32_e32 v211, 16, v219
	v_and_b32_e32 v212, 0xffff0000, v212
	v_and_b32_e32 v213, 0xffff0000, v213
	v_and_b32_e32 v214, 0xffff0000, v214
	v_and_b32_e32 v215, 0xffff0000, v215
	v_and_b32_e32 v216, 0xffff0000, v216
	v_and_b32_e32 v217, 0xffff0000, v217
	v_and_b32_e32 v218, 0xffff0000, v218
	v_and_b32_e32 v219, 0xffff0000, v219
	v_add_f32_e32 v12, v12, v204
	v_add_f32_e32 v13, v13, v212
	v_add_f32_e32 v14, v14, v205
	v_add_f32_e32 v15, v15, v213
	v_add_f32_e32 v8, v8, v206
	v_add_f32_e32 v9, v9, v214
	v_add_f32_e32 v10, v10, v207
	v_add_f32_e32 v11, v11, v215
	v_add_f32_e32 v4, v4, v208
	v_add_f32_e32 v5, v5, v216
	v_add_f32_e32 v6, v6, v209
	v_add_f32_e32 v7, v7, v217
	v_add_f32_e32 v0, v0, v210
	v_add_f32_e32 v1, v1, v218
	v_add_f32_e32 v2, v2, v211
	v_add_f32_e32 v3, v3, v219
	v_mul_f32_e32 v204, v12, v12
	v_mul_f32_e32 v205, v8, v8
	v_mul_f32_e32 v206, v4, v4
	v_mul_f32_e32 v207, v0, v0
	v_fmac_f32_e32 v204, v13, v13
	v_fmac_f32_e32 v205, v9, v9
	v_fmac_f32_e32 v206, v5, v5
	v_fmac_f32_e32 v207, v1, v1
	v_fmac_f32_e32 v204, v14, v14
	v_fmac_f32_e32 v205, v10, v10
	v_fmac_f32_e32 v206, v6, v6
	v_fmac_f32_e32 v207, v2, v2
	v_fmac_f32_e32 v204, v15, v15
	v_fmac_f32_e32 v205, v11, v11
	v_fmac_f32_e32 v206, v7, v7
	v_fmac_f32_e32 v207, v3, v3
	v_cvt_pk_bf16_f32 v12, v12, v13
	v_cvt_pk_bf16_f32 v13, v14, v15
	v_cvt_pk_bf16_f32 v14, v8, v9
	v_cvt_pk_bf16_f32 v15, v10, v11
	v_cvt_pk_bf16_f32 v4, v4, v5
	v_cvt_pk_bf16_f32 v5, v6, v7
	v_cvt_pk_bf16_f32 v6, v0, v1
	v_cvt_pk_bf16_f32 v7, v2, v3
	global_store_dwordx4 v[166:167], v[12:15], off
	global_store_dwordx4 v[166:167], v[4:7], off offset:256
	v_add_f32_e32 v204, v204, v205
	v_add_f32_e32 v206, v206, v207
	v_add_f32_e32 v8, v204, v206
	v_mov_b32_e32 v125, v124
	v_mov_b32_e32 v105, v104
	v_mov_b32_e32 v89, v88
	v_mov_b32_e32 v73, v72
	v_mov_b32_e32 v57, v56
	v_mov_b32_e32 v41, v40
	v_mov_b32_e32 v25, v24
	v_mov_b32_e32 v9, v8
	v_permlane16_swap_b32_e32 v124, v125
	v_permlane16_swap_b32_e32 v104, v105
	v_permlane16_swap_b32_e32 v88, v89
	v_permlane16_swap_b32_e32 v72, v73
	v_permlane16_swap_b32_e32 v56, v57
	v_permlane16_swap_b32_e32 v40, v41
	v_permlane16_swap_b32_e32 v24, v25
	v_permlane16_swap_b32_e32 v8, v9
	v_add_f32_e32 v124, v124, v125
	v_add_f32_e32 v104, v104, v105
	v_add_f32_e32 v88, v88, v89
	v_add_f32_e32 v72, v72, v73
	v_add_f32_e32 v56, v56, v57
	v_add_f32_e32 v40, v40, v41
	v_add_f32_e32 v24, v24, v25
	v_add_f32_e32 v8, v8, v9
	v_mov_b32_e32 v125, v124
	v_mov_b32_e32 v105, v104
	v_mov_b32_e32 v89, v88
	v_mov_b32_e32 v73, v72
	v_mov_b32_e32 v57, v56
	v_mov_b32_e32 v41, v40
	v_mov_b32_e32 v25, v24
	v_mov_b32_e32 v9, v8
	v_permlane32_swap_b32_e32 v124, v125
	v_permlane32_swap_b32_e32 v104, v105
	v_permlane32_swap_b32_e32 v88, v89
	v_permlane32_swap_b32_e32 v72, v73
	v_permlane32_swap_b32_e32 v56, v57
	v_permlane32_swap_b32_e32 v40, v41
	v_permlane32_swap_b32_e32 v24, v25
	v_permlane32_swap_b32_e32 v8, v9
	v_add_f32_e32 v124, v124, v125
	v_add_f32_e32 v104, v104, v105
	v_add_f32_e32 v88, v88, v89
	v_add_f32_e32 v72, v72, v73
	v_add_f32_e32 v56, v56, v57
	v_add_f32_e32 v40, v40, v41
	v_add_f32_e32 v24, v24, v25
	v_add_f32_e32 v8, v8, v9
	s_mov_b32 s100, 0x2000
	v_cmp_eq_u32_e32 vcc, 0, v185
	v_lshl_add_u64 v[202:203], v[200:201], 0, s[100:101]
	s_and_saveexec_b64 s[28:29], vcc
	global_store_dword v[200:201], v124, off
	global_store_dword v[200:201], v104, off offset:1024
	global_store_dword v[200:201], v88, off offset:2048
	global_store_dword v[200:201], v72, off offset:3072
	global_store_dword v[202:203], v56, off
	global_store_dword v[202:203], v40, off offset:1024
	global_store_dword v[202:203], v24, off offset:2048
	global_store_dword v[202:203], v8, off offset:3072
	s_or_b64 exec, exec, s[28:29]
	s_and_b64 vcc, exec, s[6:7]
	s_mov_b64 s[0:1], -1
	s_cbranch_vccnz .LBB0_340
	s_andn2_b64 vcc, exec, s[20:21]
	s_cbranch_vccnz .LBB0_339
	s_barrier
	s_branch .LBB0_339

;     __host__ __device__ bool next(int i, Unit& u) const {
;         const long L = (long)i * G + c; if (L >= nwg) return false;
;         int wgid = (int)L; { const int q = nwg / NXCD, r = nwg % NXCD, xcd = wgid % NXCD, off = wgid / NXCD; wgid = (xcd < r ? xcd * (q + 1) : r * (q + 1) + (xcd - r) * q) + off; }
;         const int nig = WGM * nN, gid = wgid / nig, fm = gid * WGM, gsz = (nM - fm) < WGM ? (nM - fm) : WGM;
;         u.pm = fm + ((wgid % nig) % gsz); u.pn = (wgid % nig) / gsz; return true;
;     }
.LBB0_404:
	s_cmp_lg_u32 s88, 0x100
	s_cbranch_scc1 .Lsn_gen_2
	s_add_i32 s52, s52, 1
	s_cmp_lt_u32 s52, 22
	s_cselect_b64 s[8:9], -1, 0
	s_cbranch_scc0 .LBB0_406
	s_add_i32 s53, s2, 4
	s_mov_b32 s54, s0
	s_cmp_lt_u32 s53, 22
	s_cbranch_scc1 .LBB0_406
	s_sub_i32 s53, s53, 22
	s_add_i32 s54, s54, 8
	s_branch .LBB0_406

;     __host__ __device__ bool next(int i, Unit& u) const {
;         const long L = (long)i * G + c; if (L >= nwg) return false;
;         int wgid = (int)L; { const int q = nwg / NXCD, r = nwg % NXCD, xcd = wgid % NXCD, off = wgid / NXCD; wgid = (xcd < r ? xcd * (q + 1) : r * (q + 1) + (xcd - r) * q) + off; }
;         const int nig = WGM * nN, gid = wgid / nig, fm = gid * WGM, gsz = (nM - fm) < WGM ? (nM - fm) : WGM;
;         u.pm = fm + ((wgid % nig) % gsz); u.pn = (wgid % nig) / gsz; return true;
;     }
.LBB0_452:
	s_cmp_lg_u32 s88, 0x100
	s_cbranch_scc1 .Lsn_gen_3
	s_add_i32 s43, s43, 1
	s_cmp_lt_u32 s43, 4
	s_cselect_b64 s[8:9], -1, 0
	s_cbranch_scc0 .LBB0_458
	s_add_i32 s44, s46, 4
	s_mov_b32 s45, s47
	s_cmp_lt_u32 s44, 4
	s_cbranch_scc1 .LBB0_458
	s_sub_i32 s44, s44, 4
	s_add_i32 s45, s45, 8
	s_branch .LBB0_458

;     __host__ __device__ bool next(int i, Unit& u) const {
;         const long L = (long)i * G + c; if (L >= nwg) return false;
;         int wgid = (int)L; { const int q = nwg / NXCD, r = nwg % NXCD, xcd = wgid % NXCD, off = wgid / NXCD; wgid = (xcd < r ? xcd * (q + 1) : r * (q + 1) + (xcd - r) * q) + off; }
;         const int nig = WGM * nN, gid = wgid / nig, fm = gid * WGM, gsz = (nM - fm) < WGM ? (nM - fm) : WGM;
;         u.pm = fm + ((wgid % nig) % gsz); u.pn = (wgid % nig) / gsz; return true;
;     }
.LBB0_485:
	s_cmp_lg_u32 s88, 0x100
	s_cbranch_scc1 .Lsn_gen_4
	s_add_i32 s44, s44, 1
	s_cmp_lt_u32 s44, 4
	s_cselect_b64 s[8:9], -1, 0
	s_cbranch_scc0 .LBB0_491
	s_add_i32 s45, s2, 4
	s_mov_b32 s46, s47
	s_cmp_lt_u32 s45, 4
	s_cbranch_scc1 .LBB0_491
	s_sub_i32 s45, s45, 4
	s_add_i32 s46, s46, 8
	s_branch .LBB0_491

; __device__ __forceinline__ unsigned cvt_pk_bf16(float lo, float hi) { unsigned r; asm volatile("v_cvt_pk_bf16_f32 %0, %1, %2" : "=v"(r) : "v"(lo), "v"(hi)); return r; }
; __device__ __forceinline__ float bf_lo(unsigned w) { return __uint_as_float(w << 16); }
;     __device__ __forceinline__ void operator()(const f32x4 (&acc)[2][2][4][2], const pg8::Unit& u, int wr, int wc, int fr_, int fq_, LAS const unsigned char* xl) const {
;     ...
;                     for (int bj = 0; bj < 2; ++bj) { const size_t off = (size_t)(row0 + ai * 128 + (mb + m) * 16) * DM + col + bj * 128;
;                         hw[m][bj] = *(const u32x4*)(h_old + off); if (MODE == 4) pw[m][bj] = *(const u32x4*)(pp + off); }
; #pragma unroll
;                 for (int mm = 0; mm < MB; ++mm) {
;                     const int m = mb + mm;
;                     const int row = row0 + ai * 128 + m * 16; const float rinv = rv[ai][m];
;                     float ss = 0.f;
; #pragma unroll
;                     for (int bj = 0; bj < 2; ++bj) { const size_t off = (size_t)row * DM + col + bj * 128;
;                         const u32x4 h4 = hw[mm][bj];
;                         f32x4 a = {bf_lo(h4.x), bf_hi(h4.x), bf_lo(h4.y), bf_hi(h4.y)}, b = {bf_lo(h4.z), bf_hi(h4.z), bf_lo(h4.w), bf_hi(h4.w)};
;                         f32x4 d0 = acc[ai][bj][m][0], d1 = acc[ai][bj][m][1];
;                         if (MODE == 4) { const u32x4 p4 = pw[mm][bj];
;                             d0[0] = fast_sigmoid(d0[0] * rinv) * bf_lo(p4.x); d0[1] = fast_sigmoid(d0[1] * rinv) * bf_hi(p4.x);
;                             d0[2] = fast_sigmoid(d0[2] * rinv) * bf_lo(p4.y); d0[3] = fast_sigmoid(d0[3] * rinv) * bf_hi(p4.y);
;                             d1[0] = fast_sigmoid(d1[0] * rinv) * bf_lo(p4.z); d1[1] = fast_sigmoid(d1[1] * rinv) * bf_hi(p4.z);
;                             d1[2] = fast_sigmoid(d1[2] * rinv) * bf_lo(p4.w); d1[3] = fast_sigmoid(d1[3] * rinv) * bf_hi(p4.w); }
;                         a += d0; b += d1;
;                         u32x4 w; w.x = pg8::cvt_pk_bf16(a[0], a[1]); w.y = pg8::cvt_pk_bf16(a[2], a[3]); w.z = pg8::cvt_pk_bf16(b[0], b[1]); w.w = pg8::cvt_pk_bf16(b[2], b[3]);
;                         *(u32x4*)(O + off) = w;
;                         ss += (a[0] * a[0] + a[1] * a[1]) + (a[2] * a[2] + a[3] * a[3]) + (b[0] * b[0] + b[1] * b[1]) + (b[2] * b[2] + b[3] * b[3]); }
.LBB0_500:
	s_lshl_b32 s0, s47, 8
	s_add_i32 s0, s0, s39
	v_readlane_b32 s26, v255, 24
	v_readlane_b32 s27, v255, 25
	v_readlane_b32 s48, v255, 26
	v_readlane_b32 s49, v255, 27
	v_add_u32_e32 v200, s0, v184
	s_lshl_b32 s0, s2, 8
	s_or_b32 s0, s0, s40
	v_lshl_add_u32 v201, v185, 3, s0
	v_lshlrev_b32_e32 v202, 11, v200
	v_lshl_or_b32 v202, v201, 1, v202
	v_mov_b32_e32 v203, 0
	s_mov_b32 s100, 0x8000
	s_mov_b32 s101, 0
	s_lshl_b32 s0, s2, 4
	s_lshl_b32 s86, s37, 2
	s_add_i32 s86, s86, s0
	s_mov_b32 s0, 0x28000
	s_mov_b32 s1, 0
	v_lshl_add_u64 v[194:195], s[26:27], 0, v[202:203]
	global_load_dwordx4 v[128:131], v[194:195], off
	global_load_dwordx4 v[132:135], v[194:195], off offset:256
	v_lshl_add_u64 v[166:167], v[194:195], 0, s[100:101]
	global_load_dwordx4 v[136:139], v[166:167], off
	global_load_dwordx4 v[140:143], v[166:167], off offset:256
	v_lshl_add_u64 v[194:195], v[166:167], 0, s[100:101]
	global_load_dwordx4 v[144:147], v[194:195], off
	global_load_dwordx4 v[148:151], v[194:195], off offset:256
	v_lshl_add_u64 v[166:167], v[194:195], 0, s[100:101]
	global_load_dwordx4 v[152:155], v[166:167], off
	global_load_dwordx4 v[168:171], v[166:167], off offset:256
	v_lshl_add_u64 v[194:195], v[166:167], 0, s[0:1]
	global_load_dwordx4 v[172:175], v[194:195], off
	global_load_dwordx4 v[176:179], v[194:195], off offset:256
	v_lshl_add_u64 v[166:167], v[194:195], 0, s[100:101]
	global_load_dwordx4 v[180:183], v[166:167], off
	global_load_dwordx4 v[188:191], v[166:167], off offset:256
	v_lshl_add_u64 v[194:195], v[166:167], 0, s[100:101]
	global_load_dwordx4 v[204:207], v[194:195], off
	global_load_dwordx4 v[208:211], v[194:195], off offset:256
	v_lshl_add_u64 v[166:167], v[194:195], 0, s[100:101]
	v_lshlrev_b32_e32 v200, 6, v200
	v_add_u32_e32 v200, s86, v200
	v_mov_b32_e32 v201, 0
	v_lshl_add_u64 v[200:201], s[48:49], 0, v[200:201]
	v_lshl_add_u64 v[194:195], s[26:27], 0, v[202:203]
	s_waitcnt vmcnt(12)
	v_lshlrev_b32_e32 v212, 16, v128
	v_lshlrev_b32_e32 v213, 16, v129
	v_lshlrev_b32_e32 v214, 16, v130
	v_lshlrev_b32_e32 v215, 16, v131
	v_lshlrev_b32_e32 v216, 16, v132
	v_lshlrev_b32_e32 v217, 16, v133
	v_lshlrev_b32_e32 v218, 16, v134
	v_lshlrev_b32_e32 v219, 16, v135
	v_and_b32_e32 v128, 0xffff0000, v128
	v_and_b32_e32 v129, 0xffff0000, v129
	v_and_b32_e32 v130, 0xffff0000, v130
	v_and_b32_e32 v131, 0xffff0000, v131
	v_and_b32_e32 v132, 0xffff0000, v132
	v_and_b32_e32 v133, 0xffff0000, v133
	v_and_b32_e32 v134, 0xffff0000, v134
	v_and_b32_e32 v135, 0xffff0000, v135
	v_add_f32_e32 v120, v120, v212
	v_add_f32_e32 v121, v121, v128
	v_add_f32_e32 v122, v122, v213
	v_add_f32_e32 v123, v123, v129
	v_add_f32_e32 v124, v124, v214
	v_add_f32_e32 v125, v125, v130
	v_add_f32_e32 v126, v126, v215
	v_add_f32_e32 v127, v127, v131
	v_add_f32_e32 v116, v116, v216
	v_add_f32_e32 v117, v117, v132
	v_add_f32_e32 v118, v118, v217
	v_add_f32_e32 v119, v119, v133
	v_add_f32_e32 v112, v112, v218
	v_add_f32_e32 v113, v113, v134
	v_add_f32_e32 v114, v114, v219
	v_add_f32_e32 v115, v115, v135
	v_mul_f32_e32 v212, v120, v120
	v_mul_f32_e32 v213, v124, v124
	v_mul_f32_e32 v214, v116, v116
	v_mul_f32_e32 v215, v112, v112
	v_fmac_f32_e32 v212, v121, v121
	v_fmac_f32_e32 v213, v125, v125
	v_fmac_f32_e32 v214, v117, v117
	v_fmac_f32_e32 v215, v113, v113
	v_fmac_f32_e32 v212, v122, v122
	v_fmac_f32_e32 v213, v126, v126
	v_fmac_f32_e32 v214, v118, v118
	v_fmac_f32_e32 v215, v114, v114
	v_fmac_f32_e32 v212, v123, v123
	v_fmac_f32_e32 v213, v127, v127
	v_fmac_f32_e32 v214, v119, v119
	v_fmac_f32_e32 v215, v115, v115
	v_cvt_pk_bf16_f32 v120, v120, v121
	v_cvt_pk_bf16_f32 v121, v122, v123
	v_cvt_pk_bf16_f32 v122, v124, v125
	v_cvt_pk_bf16_f32 v123, v126, v127
	v_cvt_pk_bf16_f32 v116, v116, v117
	v_cvt_pk_bf16_f32 v117, v118, v119
	v_cvt_pk_bf16_f32 v118, v112, v113
	v_cvt_pk_bf16_f32 v119, v114, v115
	global_store_dwordx4 v[194:195], v[120:123], off
	global_store_dwordx4 v[194:195], v[116:119], off offset:256
	v_add_f32_e32 v212, v212, v213
	v_add_f32_e32 v214, v214, v215
	v_add_f32_e32 v124, v212, v214
	global_load_dwordx4 v[212:215], v[166:167], off
	global_load_dwordx4 v[216:219], v[166:167], off offset:256
	v_lshl_add_u64 v[166:167], v[194:195], 0, s[100:101]
	s_waitcnt vmcnt(14)
	v_lshlrev_b32_e32 v128, 16, v136
	v_lshlrev_b32_e32 v129, 16, v137
	v_lshlrev_b32_e32 v130, 16, v138
	v_lshlrev_b32_e32 v131, 16, v139
	v_lshlrev_b32_e32 v132, 16, v140
	v_lshlrev_b32_e32 v133, 16, v141
	v_lshlrev_b32_e32 v134, 16, v142
	v_lshlrev_b32_e32 v135, 16, v143
	v_and_b32_e32 v136, 0xffff0000, v136
	v_and_b32_e32 v137, 0xffff0000, v137
	v_and_b32_e32 v138, 0xffff0000, v138
	v_and_b32_e32 v139, 0xffff0000, v139
	v_and_b32_e32 v140, 0xffff0000, v140
	v_and_b32_e32 v141, 0xffff0000, v141
	v_and_b32_e32 v142, 0xffff0000, v142
	v_and_b32_e32 v143, 0xffff0000, v143
	v_add_f32_e32 v108, v108, v128
	v_add_f32_e32 v109, v109, v136
	v_add_f32_e32 v110, v110, v129
	v_add_f32_e32 v111, v111, v137
	v_add_f32_e32 v104, v104, v130
	v_add_f32_e32 v105, v105, v138
	v_add_f32_e32 v106, v106, v131
	v_add_f32_e32 v107, v107, v139
	v_add_f32_e32 v100, v100, v132
	v_add_f32_e32 v101, v101, v140
	v_add_f32_e32 v102, v102, v133
	v_add_f32_e32 v103, v103, v141
	v_add_f32_e32 v96, v96, v134
	v_add_f32_e32 v97, v97, v142
	v_add_f32_e32 v98, v98, v135
	v_add_f32_e32 v99, v99, v143
	v_mul_f32_e32 v128, v108, v108
	v_mul_f32_e32 v129, v104, v104
	v_mul_f32_e32 v130, v100, v100
	v_mul_f32_e32 v131, v96, v96
	v_fmac_f32_e32 v128, v109, v109
	v_fmac_f32_e32 v129, v105, v105
	v_fmac_f32_e32 v130, v101, v101
	v_fmac_f32_e32 v131, v97, v97
	v_fmac_f32_e32 v128, v110, v110
	v_fmac_f32_e32 v129, v106, v106
	v_fmac_f32_e32 v130, v102, v102
	v_fmac_f32_e32 v131, v98, v98
	v_fmac_f32_e32 v128, v111, v111
	v_fmac_f32_e32 v129, v107, v107
	v_fmac_f32_e32 v130, v103, v103
	v_fmac_f32_e32 v131, v99, v99
	v_cvt_pk_bf16_f32 v108, v108, v109
	v_cvt_pk_bf16_f32 v109, v110, v111
	v_cvt_pk_bf16_f32 v110, v104, v105
	v_cvt_pk_bf16_f32 v111, v106, v107
	v_cvt_pk_bf16_f32 v100, v100, v101
	v_cvt_pk_bf16_f32 v101, v102, v103
	v_cvt_pk_bf16_f32 v102, v96, v97
	v_cvt_pk_bf16_f32 v103, v98, v99
	global_store_dwordx4 v[166:167], v[108:111], off
	global_store_dwordx4 v[166:167], v[100:103], off offset:256
	v_add_f32_e32 v128, v128, v129
	v_add_f32_e32 v130, v130, v131
	v_add_f32_e32 v104, v128, v130
	v_lshl_add_u64 v[194:195], v[166:167], 0, s[100:101]
	s_waitcnt vmcnt(14)
; __device__ __forceinline__ unsigned cvt_pk_bf16(float lo, float hi) { unsigned r; asm volatile("v_cvt_pk_bf16_f32 %0, %1, %2" : "=v"(r) : "v"(lo), "v"(hi)); return r; }
; __device__ __forceinline__ float bf_lo(unsigned w) { return __uint_as_float(w << 16); }
; __device__ __forceinline__ float bf_hi(unsigned w) { return __uint_as_float(w & 0xffff0000u); }
; __device__ __forceinline__ float fast_sigmoid(float x) { return __builtin_amdgcn_rcpf(1.0f + __expf(-x)); }
;     __device__ __forceinline__ void operator()(const f32x4 (&acc)[2][2][4][2], const pg8::Unit& u, int wr, int wc, int fr_, int fq_, LAS const unsigned char* xl) const {
;     ...
;                     for (int bj = 0; bj < 2; ++bj) { const size_t off = (size_t)row * DM + col + bj * 128;
;                         const u32x4 h4 = hw[mm][bj];
;                         f32x4 a = {bf_lo(h4.x), bf_hi(h4.x), bf_lo(h4.y), bf_hi(h4.y)}, b = {bf_lo(h4.z), bf_hi(h4.z), bf_lo(h4.w), bf_hi(h4.w)};
;                         f32x4 d0 = acc[ai][bj][m][0], d1 = acc[ai][bj][m][1];
;                         if (MODE == 4) { const u32x4 p4 = pw[mm][bj];
;                             d0[0] = fast_sigmoid(d0[0] * rinv) * bf_lo(p4.x); d0[1] = fast_sigmoid(d0[1] * rinv) * bf_hi(p4.x);
;                             d0[2] = fast_sigmoid(d0[2] * rinv) * bf_lo(p4.y); d0[3] = fast_sigmoid(d0[3] * rinv) * bf_hi(p4.y);
;                             d1[0] = fast_sigmoid(d1[0] * rinv) * bf_lo(p4.z); d1[1] = fast_sigmoid(d1[1] * rinv) * bf_hi(p4.z);
;                             d1[2] = fast_sigmoid(d1[2] * rinv) * bf_lo(p4.w); d1[3] = fast_sigmoid(d1[3] * rinv) * bf_hi(p4.w); }
;                         a += d0; b += d1;
;                         u32x4 w; w.x = pg8::cvt_pk_bf16(a[0], a[1]); w.y = pg8::cvt_pk_bf16(a[2], a[3]); w.z = pg8::cvt_pk_bf16(b[0], b[1]); w.w = pg8::cvt_pk_bf16(b[2], b[3]);
;                         *(u32x4*)(O + off) = w;
;                         ss += (a[0] * a[0] + a[1] * a[1]) + (a[2] * a[2] + a[3] * a[3]) + (b[0] * b[0] + b[1] * b[1]) + (b[2] * b[2] + b[3] * b[3]); }
	v_lshlrev_b32_e32 v136, 16, v144
	v_lshlrev_b32_e32 v137, 16, v145
	v_lshlrev_b32_e32 v138, 16, v146
	v_lshlrev_b32_e32 v139, 16, v147
	v_lshlrev_b32_e32 v140, 16, v148
	v_lshlrev_b32_e32 v141, 16, v149
	v_lshlrev_b32_e32 v142, 16, v150
	v_lshlrev_b32_e32 v143, 16, v151
	v_and_b32_e32 v144, 0xffff0000, v144
	v_and_b32_e32 v145, 0xffff0000, v145
	v_and_b32_e32 v146, 0xffff0000, v146
	v_and_b32_e32 v147, 0xffff0000, v147
	v_and_b32_e32 v148, 0xffff0000, v148
	v_and_b32_e32 v149, 0xffff0000, v149
	v_and_b32_e32 v150, 0xffff0000, v150
	v_and_b32_e32 v151, 0xffff0000, v151
	v_add_f32_e32 v92, v92, v136
	v_add_f32_e32 v93, v93, v144
	v_add_f32_e32 v94, v94, v137
	v_add_f32_e32 v95, v95, v145
	v_add_f32_e32 v88, v88, v138
	v_add_f32_e32 v89, v89, v146
	v_add_f32_e32 v90, v90, v139
	v_add_f32_e32 v91, v91, v147
	v_add_f32_e32 v84, v84, v140
	v_add_f32_e32 v85, v85, v148
	v_add_f32_e32 v86, v86, v141
	v_add_f32_e32 v87, v87, v149
	v_add_f32_e32 v80, v80, v142
	v_add_f32_e32 v81, v81, v150
	v_add_f32_e32 v82, v82, v143
	v_add_f32_e32 v83, v83, v151
	v_mul_f32_e32 v136, v92, v92
	v_mul_f32_e32 v137, v88, v88
	v_mul_f32_e32 v138, v84, v84
	v_mul_f32_e32 v139, v80, v80
	v_fmac_f32_e32 v136, v93, v93
	v_fmac_f32_e32 v137, v89, v89
	v_fmac_f32_e32 v138, v85, v85
	v_fmac_f32_e32 v139, v81, v81
	v_fmac_f32_e32 v136, v94, v94
	v_fmac_f32_e32 v137, v90, v90
	v_fmac_f32_e32 v138, v86, v86
	v_fmac_f32_e32 v139, v82, v82
	v_fmac_f32_e32 v136, v95, v95
	v_fmac_f32_e32 v137, v91, v91
	v_fmac_f32_e32 v138, v87, v87
	v_fmac_f32_e32 v139, v83, v83
	v_cvt_pk_bf16_f32 v92, v92, v93
	v_cvt_pk_bf16_f32 v93, v94, v95
	v_cvt_pk_bf16_f32 v94, v88, v89
	v_cvt_pk_bf16_f32 v95, v90, v91
	v_cvt_pk_bf16_f32 v84, v84, v85
	v_cvt_pk_bf16_f32 v85, v86, v87
	v_cvt_pk_bf16_f32 v86, v80, v81
	v_cvt_pk_bf16_f32 v87, v82, v83
	global_store_dwordx4 v[194:195], v[92:95], off
	global_store_dwordx4 v[194:195], v[84:87], off offset:256
	v_add_f32_e32 v136, v136, v137
	v_add_f32_e32 v138, v138, v139
	v_add_f32_e32 v88, v136, v138
	v_lshl_add_u64 v[166:167], v[194:195], 0, s[100:101]
	s_waitcnt vmcnt(14)
	v_lshlrev_b32_e32 v144, 16, v152
	v_lshlrev_b32_e32 v145, 16, v153
	v_lshlrev_b32_e32 v146, 16, v154
	v_lshlrev_b32_e32 v147, 16, v155
	v_lshlrev_b32_e32 v148, 16, v168
	v_lshlrev_b32_e32 v149, 16, v169
	v_lshlrev_b32_e32 v150, 16, v170
	v_lshlrev_b32_e32 v151, 16, v171
	v_and_b32_e32 v152, 0xffff0000, v152
	v_and_b32_e32 v153, 0xffff0000, v153
	v_and_b32_e32 v154, 0xffff0000, v154
	v_and_b32_e32 v155, 0xffff0000, v155
	v_and_b32_e32 v168, 0xffff0000, v168
	v_and_b32_e32 v169, 0xffff0000, v169
	v_and_b32_e32 v170, 0xffff0000, v170
	v_and_b32_e32 v171, 0xffff0000, v171
	v_add_f32_e32 v76, v76, v144
	v_add_f32_e32 v77, v77, v152
	v_add_f32_e32 v78, v78, v145
	v_add_f32_e32 v79, v79, v153
	v_add_f32_e32 v72, v72, v146
	v_add_f32_e32 v73, v73, v154
	v_add_f32_e32 v74, v74, v147
	v_add_f32_e32 v75, v75, v155
	v_add_f32_e32 v68, v68, v148
	v_add_f32_e32 v69, v69, v168
	v_add_f32_e32 v70, v70, v149
	v_add_f32_e32 v71, v71, v169
	v_add_f32_e32 v64, v64, v150
	v_add_f32_e32 v65, v65, v170
	v_add_f32_e32 v66, v66, v151
	v_add_f32_e32 v67, v67, v171
	v_mul_f32_e32 v144, v76, v76
	v_mul_f32_e32 v145, v72, v72
	v_mul_f32_e32 v146, v68, v68
	v_mul_f32_e32 v147, v64, v64
	v_fmac_f32_e32 v144, v77, v77
	v_fmac_f32_e32 v145, v73, v73
	v_fmac_f32_e32 v146, v69, v69
	v_fmac_f32_e32 v147, v65, v65
	v_fmac_f32_e32 v144, v78, v78
	v_fmac_f32_e32 v145, v74, v74
	v_fmac_f32_e32 v146, v70, v70
	v_fmac_f32_e32 v147, v66, v66
	v_fmac_f32_e32 v144, v79, v79
	v_fmac_f32_e32 v145, v75, v75
	v_fmac_f32_e32 v146, v71, v71
	v_fmac_f32_e32 v147, v67, v67
	v_cvt_pk_bf16_f32 v76, v76, v77
	v_cvt_pk_bf16_f32 v77, v78, v79
	v_cvt_pk_bf16_f32 v78, v72, v73
	v_cvt_pk_bf16_f32 v79, v74, v75
	v_cvt_pk_bf16_f32 v68, v68, v69
	v_cvt_pk_bf16_f32 v69, v70, v71
	v_cvt_pk_bf16_f32 v70, v64, v65
	v_cvt_pk_bf16_f32 v71, v66, v67
	global_store_dwordx4 v[166:167], v[76:79], off
	global_store_dwordx4 v[166:167], v[68:71], off offset:256
	v_add_f32_e32 v144, v144, v145
	v_add_f32_e32 v146, v146, v147
	v_add_f32_e32 v72, v144, v146
	v_lshl_add_u64 v[194:195], v[166:167], 0, s[0:1]
	s_waitcnt vmcnt(14)
	v_lshlrev_b32_e32 v152, 16, v172
	v_lshlrev_b32_e32 v153, 16, v173
	v_lshlrev_b32_e32 v154, 16, v174
	v_lshlrev_b32_e32 v155, 16, v175
	v_lshlrev_b32_e32 v168, 16, v176
	v_lshlrev_b32_e32 v169, 16, v177
	v_lshlrev_b32_e32 v170, 16, v178
	v_lshlrev_b32_e32 v171, 16, v179
	v_and_b32_e32 v172, 0xffff0000, v172
	v_and_b32_e32 v173, 0xffff0000, v173
	v_and_b32_e32 v174, 0xffff0000, v174
	v_and_b32_e32 v175, 0xffff0000, v175
	v_and_b32_e32 v176, 0xffff0000, v176
	v_and_b32_e32 v177, 0xffff0000, v177
	v_and_b32_e32 v178, 0xffff0000, v178
	v_and_b32_e32 v179, 0xffff0000, v179
	v_add_f32_e32 v60, v60, v152
	v_add_f32_e32 v61, v61, v172
	v_add_f32_e32 v62, v62, v153
	v_add_f32_e32 v63, v63, v173
	v_add_f32_e32 v56, v56, v154
	v_add_f32_e32 v57, v57, v174
	v_add_f32_e32 v58, v58, v155
	v_add_f32_e32 v59, v59, v175
	v_add_f32_e32 v52, v52, v168
	v_add_f32_e32 v53, v53, v176
	v_add_f32_e32 v54, v54, v169
	v_add_f32_e32 v55, v55, v177
	v_add_f32_e32 v48, v48, v170
	v_add_f32_e32 v49, v49, v178
	v_add_f32_e32 v50, v50, v171
	v_add_f32_e32 v51, v51, v179
	v_mul_f32_e32 v152, v60, v60
	v_mul_f32_e32 v153, v56, v56
	v_mul_f32_e32 v154, v52, v52
	v_mul_f32_e32 v155, v48, v48
	v_fmac_f32_e32 v152, v61, v61
	v_fmac_f32_e32 v153, v57, v57
	v_fmac_f32_e32 v154, v53, v53
	v_fmac_f32_e32 v155, v49, v49
	v_fmac_f32_e32 v152, v62, v62
	v_fmac_f32_e32 v153, v58, v58
	v_fmac_f32_e32 v154, v54, v54
	v_fmac_f32_e32 v155, v50, v50
	v_fmac_f32_e32 v152, v63, v63
	v_fmac_f32_e32 v153, v59, v59
	v_fmac_f32_e32 v154, v55, v55
	v_fmac_f32_e32 v155, v51, v51
	v_cvt_pk_bf16_f32 v60, v60, v61
	v_cvt_pk_bf16_f32 v61, v62, v63
	v_cvt_pk_bf16_f32 v62, v56, v57
	v_cvt_pk_bf16_f32 v63, v58, v59
	v_cvt_pk_bf16_f32 v52, v52, v53
	v_cvt_pk_bf16_f32 v53, v54, v55
	v_cvt_pk_bf16_f32 v54, v48, v49
	v_cvt_pk_bf16_f32 v55, v50, v51
	global_store_dwordx4 v[194:195], v[60:63], off
	global_store_dwordx4 v[194:195], v[52:55], off offset:256
	v_add_f32_e32 v152, v152, v153
	v_add_f32_e32 v154, v154, v155
	v_add_f32_e32 v56, v152, v154
	v_lshl_add_u64 v[166:167], v[194:195], 0, s[100:101]
	s_waitcnt vmcnt(14)
; __device__ __forceinline__ unsigned cvt_pk_bf16(float lo, float hi) { unsigned r; asm volatile("v_cvt_pk_bf16_f32 %0, %1, %2" : "=v"(r) : "v"(lo), "v"(hi)); return r; }
; __device__ __forceinline__ float bf_lo(unsigned w) { return __uint_as_float(w << 16); }
; __device__ __forceinline__ float bf_hi(unsigned w) { return __uint_as_float(w & 0xffff0000u); }
; __device__ __forceinline__ float fast_sigmoid(float x) { return __builtin_amdgcn_rcpf(1.0f + __expf(-x)); }
;     __device__ __forceinline__ void operator()(const f32x4 (&acc)[2][2][4][2], const pg8::Unit& u, int wr, int wc, int fr_, int fq_, LAS const unsigned char* xl) const {
;     ...
;                     for (int bj = 0; bj < 2; ++bj) { const size_t off = (size_t)row * DM + col + bj * 128;
;                         const u32x4 h4 = hw[mm][bj];
;                         f32x4 a = {bf_lo(h4.x), bf_hi(h4.x), bf_lo(h4.y), bf_hi(h4.y)}, b = {bf_lo(h4.z), bf_hi(h4.z), bf_lo(h4.w), bf_hi(h4.w)};
;                         f32x4 d0 = acc[ai][bj][m][0], d1 = acc[ai][bj][m][1];
;                         if (MODE == 4) { const u32x4 p4 = pw[mm][bj];
;                             d0[0] = fast_sigmoid(d0[0] * rinv) * bf_lo(p4.x); d0[1] = fast_sigmoid(d0[1] * rinv) * bf_hi(p4.x);
;                             d0[2] = fast_sigmoid(d0[2] * rinv) * bf_lo(p4.y); d0[3] = fast_sigmoid(d0[3] * rinv) * bf_hi(p4.y);
;                             d1[0] = fast_sigmoid(d1[0] * rinv) * bf_lo(p4.z); d1[1] = fast_sigmoid(d1[1] * rinv) * bf_hi(p4.z);
;                             d1[2] = fast_sigmoid(d1[2] * rinv) * bf_lo(p4.w); d1[3] = fast_sigmoid(d1[3] * rinv) * bf_hi(p4.w); }
;                         a += d0; b += d1;
;                         u32x4 w; w.x = pg8::cvt_pk_bf16(a[0], a[1]); w.y = pg8::cvt_pk_bf16(a[2], a[3]); w.z = pg8::cvt_pk_bf16(b[0], b[1]); w.w = pg8::cvt_pk_bf16(b[2], b[3]);
;                         *(u32x4*)(O + off) = w;
;                         ss += (a[0] * a[0] + a[1] * a[1]) + (a[2] * a[2] + a[3] * a[3]) + (b[0] * b[0] + b[1] * b[1]) + (b[2] * b[2] + b[3] * b[3]); }
	v_lshlrev_b32_e32 v172, 16, v180
	v_lshlrev_b32_e32 v173, 16, v181
	v_lshlrev_b32_e32 v174, 16, v182
	v_lshlrev_b32_e32 v175, 16, v183
	v_lshlrev_b32_e32 v176, 16, v188
	v_lshlrev_b32_e32 v177, 16, v189
	v_lshlrev_b32_e32 v178, 16, v190
	v_lshlrev_b32_e32 v179, 16, v191
	v_and_b32_e32 v180, 0xffff0000, v180
	v_and_b32_e32 v181, 0xffff0000, v181
	v_and_b32_e32 v182, 0xffff0000, v182
	v_and_b32_e32 v183, 0xffff0000, v183
	v_and_b32_e32 v188, 0xffff0000, v188
	v_and_b32_e32 v189, 0xffff0000, v189
	v_and_b32_e32 v190, 0xffff0000, v190
	v_and_b32_e32 v191, 0xffff0000, v191
	v_add_f32_e32 v44, v44, v172
	v_add_f32_e32 v45, v45, v180
	v_add_f32_e32 v46, v46, v173
	v_add_f32_e32 v47, v47, v181
	v_add_f32_e32 v40, v40, v174
	v_add_f32_e32 v41, v41, v182
	v_add_f32_e32 v42, v42, v175
	v_add_f32_e32 v43, v43, v183
	v_add_f32_e32 v36, v36, v176
	v_add_f32_e32 v37, v37, v188
	v_add_f32_e32 v38, v38, v177
	v_add_f32_e32 v39, v39, v189
	v_add_f32_e32 v32, v32, v178
	v_add_f32_e32 v33, v33, v190
	v_add_f32_e32 v34, v34, v179
	v_add_f32_e32 v35, v35, v191
	v_mul_f32_e32 v172, v44, v44
	v_mul_f32_e32 v173, v40, v40
	v_mul_f32_e32 v174, v36, v36
	v_mul_f32_e32 v175, v32, v32
	v_fmac_f32_e32 v172, v45, v45
	v_fmac_f32_e32 v173, v41, v41
	v_fmac_f32_e32 v174, v37, v37
	v_fmac_f32_e32 v175, v33, v33
	v_fmac_f32_e32 v172, v46, v46
	v_fmac_f32_e32 v173, v42, v42
	v_fmac_f32_e32 v174, v38, v38
	v_fmac_f32_e32 v175, v34, v34
	v_fmac_f32_e32 v172, v47, v47
	v_fmac_f32_e32 v173, v43, v43
	v_fmac_f32_e32 v174, v39, v39
	v_fmac_f32_e32 v175, v35, v35
	v_cvt_pk_bf16_f32 v44, v44, v45
	v_cvt_pk_bf16_f32 v45, v46, v47
	v_cvt_pk_bf16_f32 v46, v40, v41
	v_cvt_pk_bf16_f32 v47, v42, v43
	v_cvt_pk_bf16_f32 v36, v36, v37
	v_cvt_pk_bf16_f32 v37, v38, v39
	v_cvt_pk_bf16_f32 v38, v32, v33
	v_cvt_pk_bf16_f32 v39, v34, v35
	global_store_dwordx4 v[166:167], v[44:47], off
	global_store_dwordx4 v[166:167], v[36:39], off offset:256
	v_add_f32_e32 v172, v172, v173
	v_add_f32_e32 v174, v174, v175
	v_add_f32_e32 v40, v172, v174
	v_lshl_add_u64 v[194:195], v[166:167], 0, s[100:101]
	s_waitcnt vmcnt(14)
	v_lshlrev_b32_e32 v180, 16, v204
	v_lshlrev_b32_e32 v181, 16, v205
	v_lshlrev_b32_e32 v182, 16, v206
	v_lshlrev_b32_e32 v183, 16, v207
	v_lshlrev_b32_e32 v188, 16, v208
	v_lshlrev_b32_e32 v189, 16, v209
	v_lshlrev_b32_e32 v190, 16, v210
	v_lshlrev_b32_e32 v191, 16, v211
	v_and_b32_e32 v204, 0xffff0000, v204
	v_and_b32_e32 v205, 0xffff0000, v205
	v_and_b32_e32 v206, 0xffff0000, v206
	v_and_b32_e32 v207, 0xffff0000, v207
	v_and_b32_e32 v208, 0xffff0000, v208
	v_and_b32_e32 v209, 0xffff0000, v209
	v_and_b32_e32 v210, 0xffff0000, v210
	v_and_b32_e32 v211, 0xffff0000, v211
	v_add_f32_e32 v28, v28, v180
	v_add_f32_e32 v29, v29, v204
	v_add_f32_e32 v30, v30, v181
	v_add_f32_e32 v31, v31, v205
	v_add_f32_e32 v24, v24, v182
	v_add_f32_e32 v25, v25, v206
	v_add_f32_e32 v26, v26, v183
	v_add_f32_e32 v27, v27, v207
	v_add_f32_e32 v20, v20, v188
	v_add_f32_e32 v21, v21, v208
	v_add_f32_e32 v22, v22, v189
	v_add_f32_e32 v23, v23, v209
	v_add_f32_e32 v16, v16, v190
	v_add_f32_e32 v17, v17, v210
	v_add_f32_e32 v18, v18, v191
	v_add_f32_e32 v19, v19, v211
	v_mul_f32_e32 v180, v28, v28
	v_mul_f32_e32 v181, v24, v24
	v_mul_f32_e32 v182, v20, v20
	v_mul_f32_e32 v183, v16, v16
	v_fmac_f32_e32 v180, v29, v29
	v_fmac_f32_e32 v181, v25, v25
	v_fmac_f32_e32 v182, v21, v21
	v_fmac_f32_e32 v183, v17, v17
	v_fmac_f32_e32 v180, v30, v30
	v_fmac_f32_e32 v181, v26, v26
	v_fmac_f32_e32 v182, v22, v22
	v_fmac_f32_e32 v183, v18, v18
	v_fmac_f32_e32 v180, v31, v31
	v_fmac_f32_e32 v181, v27, v27
	v_fmac_f32_e32 v182, v23, v23
	v_fmac_f32_e32 v183, v19, v19
	v_cvt_pk_bf16_f32 v28, v28, v29
	v_cvt_pk_bf16_f32 v29, v30, v31
	v_cvt_pk_bf16_f32 v30, v24, v25
	v_cvt_pk_bf16_f32 v31, v26, v27
	v_cvt_pk_bf16_f32 v20, v20, v21
	v_cvt_pk_bf16_f32 v21, v22, v23
	v_cvt_pk_bf16_f32 v22, v16, v17
	v_cvt_pk_bf16_f32 v23, v18, v19
	global_store_dwordx4 v[194:195], v[28:31], off
	global_store_dwordx4 v[194:195], v[20:23], off offset:256
	v_add_f32_e32 v180, v180, v181
	v_add_f32_e32 v182, v182, v183
	v_add_f32_e32 v24, v180, v182
	v_lshl_add_u64 v[166:167], v[194:195], 0, s[100:101]
	s_waitcnt vmcnt(12)
; __device__ __forceinline__ unsigned cvt_pk_bf16(float lo, float hi) { unsigned r; asm volatile("v_cvt_pk_bf16_f32 %0, %1, %2" : "=v"(r) : "v"(lo), "v"(hi)); return r; }
; __device__ __forceinline__ float bf_lo(unsigned w) { return __uint_as_float(w << 16); }
; __device__ __forceinline__ float bf_hi(unsigned w) { return __uint_as_float(w & 0xffff0000u); }
; __device__ __forceinline__ float fast_sigmoid(float x) { return __builtin_amdgcn_rcpf(1.0f + __expf(-x)); }
;     __device__ __forceinline__ void operator()(const f32x4 (&acc)[2][2][4][2], const pg8::Unit& u, int wr, int wc, int fr_, int fq_, LAS const unsigned char* xl) const {
;     ...
;                     for (int bj = 0; bj < 2; ++bj) { const size_t off = (size_t)row * DM + col + bj * 128;
;                         const u32x4 h4 = hw[mm][bj];
;                         f32x4 a = {bf_lo(h4.x), bf_hi(h4.x), bf_lo(h4.y), bf_hi(h4.y)}, b = {bf_lo(h4.z), bf_hi(h4.z), bf_lo(h4.w), bf_hi(h4.w)};
;                         f32x4 d0 = acc[ai][bj][m][0], d1 = acc[ai][bj][m][1];
;                         if (MODE == 4) { const u32x4 p4 = pw[mm][bj];
;                             d0[0] = fast_sigmoid(d0[0] * rinv) * bf_lo(p4.x); d0[1] = fast_sigmoid(d0[1] * rinv) * bf_hi(p4.x);
;                             d0[2] = fast_sigmoid(d0[2] * rinv) * bf_lo(p4.y); d0[3] = fast_sigmoid(d0[3] * rinv) * bf_hi(p4.y);
;                             d1[0] = fast_sigmoid(d1[0] * rinv) * bf_lo(p4.z); d1[1] = fast_sigmoid(d1[1] * rinv) * bf_hi(p4.z);
;                             d1[2] = fast_sigmoid(d1[2] * rinv) * bf_lo(p4.w); d1[3] = fast_sigmoid(d1[3] * rinv) * bf_hi(p4.w); }
;                         a += d0; b += d1;
;                         u32x4 w; w.x = pg8::cvt_pk_bf16(a[0], a[1]); w.y = pg8::cvt_pk_bf16(a[2], a[3]); w.z = pg8::cvt_pk_bf16(b[0], b[1]); w.w = pg8::cvt_pk_bf16(b[2], b[3]);
;                         *(u32x4*)(O + off) = w;
;                         ss += (a[0] * a[0] + a[1] * a[1]) + (a[2] * a[2] + a[3] * a[3]) + (b[0] * b[0] + b[1] * b[1]) + (b[2] * b[2] + b[3] * b[3]); }
;                     ss = xrow16_sum(ss);
;                     if (fq == 0) part_out[(size_t)row * 16 + u.pn * 4 + wc] = ss;
	v_lshlrev_b32_e32 v204, 16, v212
	v_lshlrev_b32_e32 v205, 16, v213
	v_lshlrev_b32_e32 v206, 16, v214
	v_lshlrev_b32_e32 v207, 16, v215
	v_lshlrev_b32_e32 v208, 16, v216
	v_lshlrev_b32_e32 v209, 16, v217
	v_lshlrev_b32_e32 v210, 16, v218
	v_lshlrev_b32_e32 v211, 16, v219
	v_and_b32_e32 v212, 0xffff0000, v212
	v_and_b32_e32 v213, 0xffff0000, v213
	v_and_b32_e32 v214, 0xffff0000, v214
	v_and_b32_e32 v215, 0xffff0000, v215
	v_and_b32_e32 v216, 0xffff0000, v216
	v_and_b32_e32 v217, 0xffff0000, v217
	v_and_b32_e32 v218, 0xffff0000, v218
	v_and_b32_e32 v219, 0xffff0000, v219
	v_add_f32_e32 v12, v12, v204
	v_add_f32_e32 v13, v13, v212
	v_add_f32_e32 v14, v14, v205
	v_add_f32_e32 v15, v15, v213
	v_add_f32_e32 v8, v8, v206
	v_add_f32_e32 v9, v9, v214
	v_add_f32_e32 v10, v10, v207
	v_add_f32_e32 v11, v11, v215
	v_add_f32_e32 v4, v4, v208
	v_add_f32_e32 v5, v5, v216
	v_add_f32_e32 v6, v6, v209
	v_add_f32_e32 v7, v7, v217
	v_add_f32_e32 v0, v0, v210
	v_add_f32_e32 v1, v1, v218
	v_add_f32_e32 v2, v2, v211
	v_add_f32_e32 v3, v3, v219
	v_mul_f32_e32 v204, v12, v12
	v_mul_f32_e32 v205, v8, v8
	v_mul_f32_e32 v206, v4, v4
	v_mul_f32_e32 v207, v0, v0
	v_fmac_f32_e32 v204, v13, v13
	v_fmac_f32_e32 v205, v9, v9
	v_fmac_f32_e32 v206, v5, v5
	v_fmac_f32_e32 v207, v1, v1
	v_fmac_f32_e32 v204, v14, v14
	v_fmac_f32_e32 v205, v10, v10
	v_fmac_f32_e32 v206, v6, v6
	v_fmac_f32_e32 v207, v2, v2
	v_fmac_f32_e32 v204, v15, v15
	v_fmac_f32_e32 v205, v11, v11
	v_fmac_f32_e32 v206, v7, v7
	v_fmac_f32_e32 v207, v3, v3
	v_cvt_pk_bf16_f32 v12, v12, v13
	v_cvt_pk_bf16_f32 v13, v14, v15
	v_cvt_pk_bf16_f32 v14, v8, v9
	v_cvt_pk_bf16_f32 v15, v10, v11
	v_cvt_pk_bf16_f32 v4, v4, v5
	v_cvt_pk_bf16_f32 v5, v6, v7
	v_cvt_pk_bf16_f32 v6, v0, v1
	v_cvt_pk_bf16_f32 v7, v2, v3
	global_store_dwordx4 v[166:167], v[12:15], off
	global_store_dwordx4 v[166:167], v[4:7], off offset:256
	v_add_f32_e32 v204, v204, v205
	v_add_f32_e32 v206, v206, v207
	v_add_f32_e32 v8, v204, v206
	v_mov_b32_e32 v125, v124
	v_mov_b32_e32 v105, v104
	v_mov_b32_e32 v89, v88
	v_mov_b32_e32 v73, v72
	v_mov_b32_e32 v57, v56
	v_mov_b32_e32 v41, v40
	v_mov_b32_e32 v25, v24
	v_mov_b32_e32 v9, v8
	v_permlane16_swap_b32_e32 v124, v125
	v_permlane16_swap_b32_e32 v104, v105
	v_permlane16_swap_b32_e32 v88, v89
	v_permlane16_swap_b32_e32 v72, v73
	v_permlane16_swap_b32_e32 v56, v57
	v_permlane16_swap_b32_e32 v40, v41
	v_permlane16_swap_b32_e32 v24, v25
	v_permlane16_swap_b32_e32 v8, v9
	v_add_f32_e32 v124, v124, v125
	v_add_f32_e32 v104, v104, v105
	v_add_f32_e32 v88, v88, v89
	v_add_f32_e32 v72, v72, v73
	v_add_f32_e32 v56, v56, v57
	v_add_f32_e32 v40, v40, v41
	v_add_f32_e32 v24, v24, v25
	v_add_f32_e32 v8, v8, v9
	v_mov_b32_e32 v125, v124
	v_mov_b32_e32 v105, v104
	v_mov_b32_e32 v89, v88
	v_mov_b32_e32 v73, v72
	v_mov_b32_e32 v57, v56
	v_mov_b32_e32 v41, v40
	v_mov_b32_e32 v25, v24
	v_mov_b32_e32 v9, v8
	v_permlane32_swap_b32_e32 v124, v125
	v_permlane32_swap_b32_e32 v104, v105
	v_permlane32_swap_b32_e32 v88, v89
	v_permlane32_swap_b32_e32 v72, v73
	v_permlane32_swap_b32_e32 v56, v57
	v_permlane32_swap_b32_e32 v40, v41
	v_permlane32_swap_b32_e32 v24, v25
	v_permlane32_swap_b32_e32 v8, v9
	v_add_f32_e32 v124, v124, v125
	v_add_f32_e32 v104, v104, v105
	v_add_f32_e32 v88, v88, v89
	v_add_f32_e32 v72, v72, v73
	v_add_f32_e32 v56, v56, v57
	v_add_f32_e32 v40, v40, v41
	v_add_f32_e32 v24, v24, v25
	v_add_f32_e32 v8, v8, v9
	s_mov_b32 s100, 0x2000
	v_cmp_eq_u32_e32 vcc, 0, v185
	v_lshl_add_u64 v[202:203], v[200:201], 0, s[100:101]
	s_and_saveexec_b64 s[26:27], vcc
	global_store_dword v[200:201], v124, off
	global_store_dword v[200:201], v104, off offset:1024
	global_store_dword v[200:201], v88, off offset:2048
	global_store_dword v[200:201], v72, off offset:3072
	global_store_dword v[202:203], v56, off
	global_store_dword v[202:203], v40, off offset:1024
	global_store_dword v[202:203], v24, off offset:2048
	global_store_dword v[202:203], v8, off offset:3072
	s_or_b64 exec, exec, s[26:27]
	s_and_b64 vcc, exec, s[6:7]
	s_mov_b64 s[0:1], -1
	s_cbranch_vccnz .LBB0_484
	s_andn2_b64 vcc, exec, s[18:19]
	s_cbranch_vccnz .LBB0_483
	s_barrier
	s_branch .LBB0_483

;     __host__ __device__ bool next(int i, Unit& u) const {
;         const long L = (long)i * G + c; if (L >= nwg) return false;
;         int wgid = (int)L; { const int q = nwg / NXCD, r = nwg % NXCD, xcd = wgid % NXCD, off = wgid / NXCD; wgid = (xcd < r ? xcd * (q + 1) : r * (q + 1) + (xcd - r) * q) + off; }
;         const int nig = WGM * nN, gid = wgid / nig, fm = gid * WGM, gsz = (nM - fm) < WGM ? (nM - fm) : WGM;
;         u.pm = fm + ((wgid % nig) % gsz); u.pn = (wgid % nig) / gsz; return true;
;     }
.LBB0_548:
	s_cmp_lg_u32 s88, 0x100
	s_cbranch_scc1 .Lsn_gen_5
	s_add_i32 s56, s56, 1
	s_cmp_lt_u32 s56, 4
	s_cselect_b64 s[6:7], -1, 0
	s_cbranch_scc0 .LBB0_554
	s_add_i32 s57, s2, 4
	s_mov_b32 s58, s0
	s_cmp_lt_u32 s57, 4
	s_cbranch_scc1 .LBB0_554
	s_sub_i32 s57, s57, 4
	s_add_i32 s58, s58, 8
	s_branch .LBB0_554
